# pooling: first and last 64-token block of a sequence also use the pipelined hand-written body (static exec masks for the clipped windows, exact 1/count), no compiler path left
# speedup vs baseline: 1.0170x; 1.0036x over previous
; #define POOL_ACC(V_, sg) do { s0 += sg bflo(V_.x); s1 += sg bfhi(V_.x); s2 += sg bflo(V_.y); s3 += sg bfhi(V_.y); s4 += sg bflo(V_.z); s5 += sg bfhi(V_.z); s6 += sg bflo(V_.w); s7 += sg bfhi(V_.w); } while (0)
; __device__ __forceinline__ void pool_phase(const bf16_t* zp, bf16_t* mixed, const int wave_s) {
;     ...
;     for (int r = blockIdx.x * 8 + wave_s; r < MTOK / 64; r += gridDim.x * 8) {
;         const int tok_base = r * 64, S = tok_base < NPROMPT ? SEQP : SEQS, pos0 = tok_base & (S - 1);
;         const bf16_t* zs = zp + (size_t)(tok_base - pos0) * 512 + c0;
;         bf16_t* ms = mixed + (size_t)(tok_base - pos0) * DM + 512 + c0;
;         float s0 = 0.f, s1 = 0.f, s2 = 0.f, s3 = 0.f, s4 = 0.f, s5 = 0.f, s6 = 0.f, s7 = 0.f;
;     ...
; #pragma unroll
;         for (int d = -8; d < 8; ++d) { const int j = pos0 + d; if (d >= -half && d < half && j >= 0 && j < S) { const u32x4 w = *(const u32x4*)(zs + (size_t)j * 512); POOL_ACC(w, +); } }
.LBB0_312:
	s_lshl_b32 s3, s23, 6
	s_cmpk_lt_i32 s23, 0x400
	s_cselect_b32 s40, s34, 0x2000
	s_add_i32 s41, s40, -1
	s_and_b32 s2, s41, s3
	s_cmp_eq_u32 s2, 0
	s_cbranch_scc1 .Lpool_first
	s_add_i32 s26, s2, 64
	s_cmp_eq_u32 s26, s40
	s_cbranch_scc1 .Lpool_last
	s_lshl_b32 s25, s3, 10
	s_add_u32 s28, s80, s25
	s_addc_u32 s29, s81, 0
	s_add_u32 s28, s28, 0x199fe000
	s_addc_u32 s29, s29, 0
	s_lshl_b32 s25, s3, 11
	s_add_u32 s30, s80, s25
	s_addc_u32 s31, s81, 0
	s_add_u32 s30, s30, 0x21a00400
	s_addc_u32 s31, s31, 0
	s_mov_b64 s[40:41], s[28:29]
	global_load_dwordx4 v[160:163], v0, s[40:41]
	global_load_dwordx4 v[168:171], v0, s[40:41] offset:1024
	global_load_dwordx4 v[172:175], v0, s[40:41] offset:2048
	global_load_dwordx4 v[180:183], v0, s[40:41] offset:3072
	s_add_u32 s40, s40, 0x1000
	s_addc_u32 s41, s41, 0
	global_load_dwordx4 v[184:187], v0, s[40:41]
	global_load_dwordx4 v[188:191], v0, s[40:41] offset:1024
	global_load_dwordx4 v[246:249], v0, s[40:41] offset:2048
	global_load_dwordx4 v[250:253], v0, s[40:41] offset:3072
	s_add_u32 s40, s40, 0x1000
	s_addc_u32 s41, s41, 0
	v_lshlrev_b32_e32 v4, 10, v26
	v_add_u32_e32 v237, 0x2000, v0
	v_add_u32_e32 v36, v237, v4
	v_sub_u32_e32 v37, v237, v4
	v_ffbl_b32_e32 v6, v26
	v_sub_u32_e32 v6, 0x7e, v6
	v_lshlrev_b32_e32 v228, 23, v6
	v_mov_b32_e32 v8, 0
	v_mov_b32_e32 v9, 0
	v_mov_b32_e32 v10, 0
	v_mov_b32_e32 v11, 0
	v_mov_b32_e32 v12, 0
	v_mov_b32_e32 v13, 0
	v_mov_b32_e32 v14, 0
	v_mov_b32_e32 v15, 0
	s_waitcnt vmcnt(7)
	s_mov_b32 exec_lo, 0
	s_mov_b32 exec_hi, 0xffff0000
	v_lshlrev_b32_e32 v4, 16, v160
	v_and_b32_e32 v6, 0xffff0000, v160
	v_lshlrev_b32_e32 v7, 16, v161
	v_and_b32_e32 v24, 0xffff0000, v161
	v_lshlrev_b32_e32 v25, 16, v162
	v_and_b32_e32 v164, 0xffff0000, v162
	v_lshlrev_b32_e32 v165, 16, v163
	v_and_b32_e32 v192, 0xffff0000, v163
	v_add_f32_e32 v8, v8, v4
	v_add_f32_e32 v9, v9, v6
	v_add_f32_e32 v10, v10, v7
	v_add_f32_e32 v11, v11, v24
	v_add_f32_e32 v12, v12, v25
	v_add_f32_e32 v13, v13, v164
	v_add_f32_e32 v14, v14, v165
	v_add_f32_e32 v15, v15, v192
	s_waitcnt vmcnt(6)
	v_lshlrev_b32_e32 v4, 16, v168
	v_and_b32_e32 v6, 0xffff0000, v168
	v_lshlrev_b32_e32 v7, 16, v169
	v_and_b32_e32 v24, 0xffff0000, v169
	v_lshlrev_b32_e32 v25, 16, v170
	v_and_b32_e32 v164, 0xffff0000, v170
	v_lshlrev_b32_e32 v165, 16, v171
	v_and_b32_e32 v192, 0xffff0000, v171
	v_add_f32_e32 v8, v8, v4
	v_add_f32_e32 v9, v9, v6
	v_add_f32_e32 v10, v10, v7
	v_add_f32_e32 v11, v11, v24
	v_add_f32_e32 v12, v12, v25
	v_add_f32_e32 v13, v13, v164
	v_add_f32_e32 v14, v14, v165
	v_add_f32_e32 v15, v15, v192
	s_waitcnt vmcnt(5)
	v_lshlrev_b32_e32 v4, 16, v172
	v_and_b32_e32 v6, 0xffff0000, v172
	v_lshlrev_b32_e32 v7, 16, v173
	v_and_b32_e32 v24, 0xffff0000, v173
	v_lshlrev_b32_e32 v25, 16, v174
	v_and_b32_e32 v164, 0xffff0000, v174
	v_lshlrev_b32_e32 v165, 16, v175
	v_and_b32_e32 v192, 0xffff0000, v175
	v_add_f32_e32 v8, v8, v4
	v_add_f32_e32 v9, v9, v6
	v_add_f32_e32 v10, v10, v7
	v_add_f32_e32 v11, v11, v24
	v_add_f32_e32 v12, v12, v25
	v_add_f32_e32 v13, v13, v164
	v_add_f32_e32 v14, v14, v165
	v_add_f32_e32 v15, v15, v192
	s_waitcnt vmcnt(4)
	v_lshlrev_b32_e32 v4, 16, v180
	v_and_b32_e32 v6, 0xffff0000, v180
	v_lshlrev_b32_e32 v7, 16, v181
	v_and_b32_e32 v24, 0xffff0000, v181
	v_lshlrev_b32_e32 v25, 16, v182
	v_and_b32_e32 v164, 0xffff0000, v182
	v_lshlrev_b32_e32 v165, 16, v183
	v_and_b32_e32 v192, 0xffff0000, v183
	v_add_f32_e32 v8, v8, v4
	v_add_f32_e32 v9, v9, v6
	v_add_f32_e32 v10, v10, v7
	v_add_f32_e32 v11, v11, v24
	v_add_f32_e32 v12, v12, v25
	v_add_f32_e32 v13, v13, v164
	v_add_f32_e32 v14, v14, v165
	v_add_f32_e32 v15, v15, v192
	s_waitcnt vmcnt(3)
	s_mov_b32 exec_lo, 0
	s_mov_b32 exec_hi, 0xffffffff
	v_lshlrev_b32_e32 v4, 16, v184
	v_and_b32_e32 v6, 0xffff0000, v184
	v_lshlrev_b32_e32 v7, 16, v185
	v_and_b32_e32 v24, 0xffff0000, v185
	v_lshlrev_b32_e32 v25, 16, v186
	v_and_b32_e32 v164, 0xffff0000, v186
	v_lshlrev_b32_e32 v165, 16, v187
	v_and_b32_e32 v192, 0xffff0000, v187
	v_add_f32_e32 v8, v8, v4
	v_add_f32_e32 v9, v9, v6
	v_add_f32_e32 v10, v10, v7
	v_add_f32_e32 v11, v11, v24
	v_add_f32_e32 v12, v12, v25
	v_add_f32_e32 v13, v13, v164
	v_add_f32_e32 v14, v14, v165
	v_add_f32_e32 v15, v15, v192
	s_waitcnt vmcnt(2)
	v_lshlrev_b32_e32 v4, 16, v188
	v_and_b32_e32 v6, 0xffff0000, v188
	v_lshlrev_b32_e32 v7, 16, v189
	v_and_b32_e32 v24, 0xffff0000, v189
	v_lshlrev_b32_e32 v25, 16, v190
	v_and_b32_e32 v164, 0xffff0000, v190
	v_lshlrev_b32_e32 v165, 16, v191
	v_and_b32_e32 v192, 0xffff0000, v191
	v_add_f32_e32 v8, v8, v4
	v_add_f32_e32 v9, v9, v6
	v_add_f32_e32 v10, v10, v7
	v_add_f32_e32 v11, v11, v24
	v_add_f32_e32 v12, v12, v25
	v_add_f32_e32 v13, v13, v164
	v_add_f32_e32 v14, v14, v165
	v_add_f32_e32 v15, v15, v192
	s_waitcnt vmcnt(1)
	s_mov_b32 exec_lo, 0xffff0000
	s_mov_b32 exec_hi, 0xffffffff
	v_lshlrev_b32_e32 v4, 16, v246
	v_and_b32_e32 v6, 0xffff0000, v246
	v_lshlrev_b32_e32 v7, 16, v247
	v_and_b32_e32 v24, 0xffff0000, v247
	v_lshlrev_b32_e32 v25, 16, v248
	v_and_b32_e32 v164, 0xffff0000, v248
	v_lshlrev_b32_e32 v165, 16, v249
	v_and_b32_e32 v192, 0xffff0000, v249
	v_add_f32_e32 v8, v8, v4
	v_add_f32_e32 v9, v9, v6
	v_add_f32_e32 v10, v10, v7
	v_add_f32_e32 v11, v11, v24
	v_add_f32_e32 v12, v12, v25
	v_add_f32_e32 v13, v13, v164
	v_add_f32_e32 v14, v14, v165
	v_add_f32_e32 v15, v15, v192
	s_waitcnt vmcnt(0)
; __device__ __forceinline__ unsigned cvt_pk_bf16(float lo, float hi) { unsigned r; asm volatile("v_cvt_pk_bf16_f32 %0, %1, %2" : "=v"(r) : "v"(lo), "v"(hi)); return r; }
; __device__ __forceinline__ float bflo(unsigned w) { return __uint_as_float(w << 16); }
; __device__ __forceinline__ float bfhi(unsigned w) { return __uint_as_float(w & 0xffff0000u); }
; #define POOL_ACC(V_, sg) do { s0 += sg bflo(V_.x); s1 += sg bfhi(V_.x); s2 += sg bflo(V_.y); s3 += sg bfhi(V_.y); s4 += sg bflo(V_.z); s5 += sg bfhi(V_.z); s6 += sg bflo(V_.w); s7 += sg bfhi(V_.w); } while (0)
; __device__ __forceinline__ void pool_phase(const bf16_t* zp, bf16_t* mixed, const int wave_s) {
;     ...
;         for (int d = -8; d < 8; ++d) { const int j = pos0 + d; if (d >= -half && d < half && j >= 0 && j < S) { const u32x4 w = *(const u32x4*)(zs + (size_t)j * 512); POOL_ACC(w, +); } }
; #pragma unroll 4
;         for (int i = 0; i < 64; ++i) {
;             const int sp = pos0 + i, lo = max(sp - half, 0), hi = min(sp + half - 1, S - 1);
;             const float ic = 1.0f / (float)(hi - lo + 1);
;             const u32x4 w = *(const u32x4*)(zs + (size_t)sp * 512);
;             u32x4 o;
;             o.x = cvt_pk_bf16(s0 * ic - bflo(w.x), s1 * ic - bfhi(w.x)); o.y = cvt_pk_bf16(s2 * ic - bflo(w.y), s3 * ic - bfhi(w.y));
;             o.z = cvt_pk_bf16(s4 * ic - bflo(w.z), s5 * ic - bfhi(w.z)); o.w = cvt_pk_bf16(s6 * ic - bflo(w.w), s7 * ic - bfhi(w.w));
;             *(u32x4*)(ms + (size_t)sp * DM) = o;
;             const int jn = sp + half, jo = sp - half;
;             if (jn < S) { const u32x4 wn = *(const u32x4*)(zs + (size_t)jn * 512); POOL_ACC(wn, +); }
;             if (jo >= 0) { const u32x4 wo = *(const u32x4*)(zs + (size_t)jo * 512); POOL_ACC(wo, -); }
	s_mov_b32 exec_lo, 0xffffffff
	s_mov_b32 exec_hi, 0xffffffff
	v_lshlrev_b32_e32 v4, 16, v250
	v_and_b32_e32 v6, 0xffff0000, v250
	v_lshlrev_b32_e32 v7, 16, v251
	v_and_b32_e32 v24, 0xffff0000, v251
	v_lshlrev_b32_e32 v25, 16, v252
	v_and_b32_e32 v164, 0xffff0000, v252
	v_lshlrev_b32_e32 v165, 16, v253
	v_and_b32_e32 v192, 0xffff0000, v253
	v_add_f32_e32 v8, v8, v4
	v_add_f32_e32 v9, v9, v6
	v_add_f32_e32 v10, v10, v7
	v_add_f32_e32 v11, v11, v24
	v_add_f32_e32 v12, v12, v25
	v_add_f32_e32 v13, v13, v164
	v_add_f32_e32 v14, v14, v165
	v_add_f32_e32 v15, v15, v192
	global_load_dwordx4 v[160:163], v0, s[40:41]
	global_load_dwordx4 v[168:171], v0, s[40:41] offset:1024
	global_load_dwordx4 v[172:175], v0, s[40:41] offset:2048
	global_load_dwordx4 v[180:183], v0, s[40:41] offset:3072
	s_add_u32 s40, s40, 0x1000
	s_addc_u32 s41, s41, 0
	global_load_dwordx4 v[184:187], v0, s[40:41]
	global_load_dwordx4 v[188:191], v0, s[40:41] offset:1024
	global_load_dwordx4 v[246:249], v0, s[40:41] offset:2048
	global_load_dwordx4 v[250:253], v0, s[40:41] offset:3072
	s_add_u32 s40, s40, 0x1000
	s_addc_u32 s41, s41, 0
	s_waitcnt vmcnt(7)
	v_lshlrev_b32_e32 v4, 16, v160
	v_and_b32_e32 v6, 0xffff0000, v160
	v_lshlrev_b32_e32 v7, 16, v161
	v_and_b32_e32 v24, 0xffff0000, v161
	v_lshlrev_b32_e32 v25, 16, v162
	v_and_b32_e32 v164, 0xffff0000, v162
	v_lshlrev_b32_e32 v165, 16, v163
	v_and_b32_e32 v192, 0xffff0000, v163
	v_add_f32_e32 v8, v8, v4
	v_add_f32_e32 v9, v9, v6
	v_add_f32_e32 v10, v10, v7
	v_add_f32_e32 v11, v11, v24
	v_add_f32_e32 v12, v12, v25
	v_add_f32_e32 v13, v13, v164
	v_add_f32_e32 v14, v14, v165
	v_add_f32_e32 v15, v15, v192
	s_waitcnt vmcnt(6)
	s_mov_b32 exec_lo, 0xffff0000
	s_mov_b32 exec_hi, 0xffffffff
	v_lshlrev_b32_e32 v4, 16, v168
	v_and_b32_e32 v6, 0xffff0000, v168
	v_lshlrev_b32_e32 v7, 16, v169
	v_and_b32_e32 v24, 0xffff0000, v169
	v_lshlrev_b32_e32 v25, 16, v170
	v_and_b32_e32 v164, 0xffff0000, v170
	v_lshlrev_b32_e32 v165, 16, v171
	v_and_b32_e32 v192, 0xffff0000, v171
	v_add_f32_e32 v8, v8, v4
	v_add_f32_e32 v9, v9, v6
	v_add_f32_e32 v10, v10, v7
	v_add_f32_e32 v11, v11, v24
	v_add_f32_e32 v12, v12, v25
	v_add_f32_e32 v13, v13, v164
	v_add_f32_e32 v14, v14, v165
	v_add_f32_e32 v15, v15, v192
	s_waitcnt vmcnt(5)
	s_mov_b32 exec_lo, 0
	s_mov_b32 exec_hi, 0xffffffff
	v_lshlrev_b32_e32 v4, 16, v172
	v_and_b32_e32 v6, 0xffff0000, v172
	v_lshlrev_b32_e32 v7, 16, v173
	v_and_b32_e32 v24, 0xffff0000, v173
	v_lshlrev_b32_e32 v25, 16, v174
	v_and_b32_e32 v164, 0xffff0000, v174
	v_lshlrev_b32_e32 v165, 16, v175
	v_and_b32_e32 v192, 0xffff0000, v175
	v_add_f32_e32 v8, v8, v4
	v_add_f32_e32 v9, v9, v6
	v_add_f32_e32 v10, v10, v7
	v_add_f32_e32 v11, v11, v24
	v_add_f32_e32 v12, v12, v25
	v_add_f32_e32 v13, v13, v164
	v_add_f32_e32 v14, v14, v165
	v_add_f32_e32 v15, v15, v192
	s_waitcnt vmcnt(4)
	v_lshlrev_b32_e32 v4, 16, v180
	v_and_b32_e32 v6, 0xffff0000, v180
	v_lshlrev_b32_e32 v7, 16, v181
	v_and_b32_e32 v24, 0xffff0000, v181
	v_lshlrev_b32_e32 v25, 16, v182
	v_and_b32_e32 v164, 0xffff0000, v182
	v_lshlrev_b32_e32 v165, 16, v183
	v_and_b32_e32 v192, 0xffff0000, v183
	v_add_f32_e32 v8, v8, v4
	v_add_f32_e32 v9, v9, v6
	v_add_f32_e32 v10, v10, v7
	v_add_f32_e32 v11, v11, v24
	v_add_f32_e32 v12, v12, v25
	v_add_f32_e32 v13, v13, v164
	v_add_f32_e32 v14, v14, v165
	v_add_f32_e32 v15, v15, v192
	s_waitcnt vmcnt(3)
	s_mov_b32 exec_lo, 0
	s_mov_b32 exec_hi, 0xffff0000
	v_lshlrev_b32_e32 v4, 16, v184
	v_and_b32_e32 v6, 0xffff0000, v184
	v_lshlrev_b32_e32 v7, 16, v185
	v_and_b32_e32 v24, 0xffff0000, v185
	v_lshlrev_b32_e32 v25, 16, v186
	v_and_b32_e32 v164, 0xffff0000, v186
	v_lshlrev_b32_e32 v165, 16, v187
	v_and_b32_e32 v192, 0xffff0000, v187
	v_add_f32_e32 v8, v8, v4
	v_add_f32_e32 v9, v9, v6
	v_add_f32_e32 v10, v10, v7
	v_add_f32_e32 v11, v11, v24
	v_add_f32_e32 v12, v12, v25
	v_add_f32_e32 v13, v13, v164
	v_add_f32_e32 v14, v14, v165
	v_add_f32_e32 v15, v15, v192
	s_waitcnt vmcnt(2)
	v_lshlrev_b32_e32 v4, 16, v188
	v_and_b32_e32 v6, 0xffff0000, v188
	v_lshlrev_b32_e32 v7, 16, v189
	v_and_b32_e32 v24, 0xffff0000, v189
	v_lshlrev_b32_e32 v25, 16, v190
	v_and_b32_e32 v164, 0xffff0000, v190
	v_lshlrev_b32_e32 v165, 16, v191
	v_and_b32_e32 v192, 0xffff0000, v191
	v_add_f32_e32 v8, v8, v4
	v_add_f32_e32 v9, v9, v6
	v_add_f32_e32 v10, v10, v7
	v_add_f32_e32 v11, v11, v24
	v_add_f32_e32 v12, v12, v25
	v_add_f32_e32 v13, v13, v164
	v_add_f32_e32 v14, v14, v165
	v_add_f32_e32 v15, v15, v192
	s_waitcnt vmcnt(1)
	v_lshlrev_b32_e32 v4, 16, v246
	v_and_b32_e32 v6, 0xffff0000, v246
	v_lshlrev_b32_e32 v7, 16, v247
	v_and_b32_e32 v24, 0xffff0000, v247
	v_lshlrev_b32_e32 v25, 16, v248
	v_and_b32_e32 v164, 0xffff0000, v248
	v_lshlrev_b32_e32 v165, 16, v249
	v_and_b32_e32 v192, 0xffff0000, v249
	v_add_f32_e32 v8, v8, v4
	v_add_f32_e32 v9, v9, v6
	v_add_f32_e32 v10, v10, v7
	v_add_f32_e32 v11, v11, v24
	v_add_f32_e32 v12, v12, v25
	v_add_f32_e32 v13, v13, v164
	v_add_f32_e32 v14, v14, v165
	v_add_f32_e32 v15, v15, v192
	s_waitcnt vmcnt(0)
	v_lshlrev_b32_e32 v4, 16, v250
	v_and_b32_e32 v6, 0xffff0000, v250
	v_lshlrev_b32_e32 v7, 16, v251
	v_and_b32_e32 v24, 0xffff0000, v251
	v_lshlrev_b32_e32 v25, 16, v252
	v_and_b32_e32 v164, 0xffff0000, v252
	v_lshlrev_b32_e32 v165, 16, v253
	v_and_b32_e32 v192, 0xffff0000, v253
	v_add_f32_e32 v8, v8, v4
	v_add_f32_e32 v9, v9, v6
	v_add_f32_e32 v10, v10, v7
	v_add_f32_e32 v11, v11, v24
	v_add_f32_e32 v12, v12, v25
	v_add_f32_e32 v13, v13, v164
	v_add_f32_e32 v14, v14, v165
	v_add_f32_e32 v15, v15, v192
	s_mov_b32 exec_lo, 0xffffffff
	s_mov_b32 exec_hi, 0xffffffff
	global_load_dwordx4 v[160:163], v237, s[28:29]
	global_load_dwordx4 v[168:171], v36, s[28:29]
	global_load_dwordx4 v[172:175], v37, s[28:29]
	global_load_dwordx4 v[180:183], v237, s[28:29] offset:1024
	global_load_dwordx4 v[184:187], v36, s[28:29] offset:1024
	global_load_dwordx4 v[188:191], v37, s[28:29] offset:1024
	global_load_dwordx4 v[246:249], v237, s[28:29] offset:2048
	global_load_dwordx4 v[250:253], v36, s[28:29] offset:2048
	global_load_dwordx4 v[20:23], v37, s[28:29] offset:2048
	global_load_dwordx4 v[28:31], v237, s[28:29] offset:3072
	global_load_dwordx4 v[32:35], v36, s[28:29] offset:3072
	global_load_dwordx4 v[16:19], v37, s[28:29] offset:3072
	s_add_u32 s28, s28, 0x1000
	s_addc_u32 s29, s29, 0
	s_mov_b32 s25, 0

; #define POOL_ACC(V_, sg) do { s0 += sg bflo(V_.x); s1 += sg bfhi(V_.x); s2 += sg bflo(V_.y); s3 += sg bfhi(V_.y); s4 += sg bflo(V_.z); s5 += sg bfhi(V_.z); s6 += sg bflo(V_.w); s7 += sg bfhi(V_.w); } while (0)
; __device__ __forceinline__ void pool_phase(const bf16_t* zp, bf16_t* mixed, const int wave_s) {
;     ...
;         const int tok_base = r * 64, S = tok_base < NPROMPT ? SEQP : SEQS, pos0 = tok_base & (S - 1);
;         const bf16_t* zs = zp + (size_t)(tok_base - pos0) * 512 + c0;
;         bf16_t* ms = mixed + (size_t)(tok_base - pos0) * DM + 512 + c0;
;         float s0 = 0.f, s1 = 0.f, s2 = 0.f, s3 = 0.f, s4 = 0.f, s5 = 0.f, s6 = 0.f, s7 = 0.f;
;     ...
; #pragma unroll
;         for (int d = -8; d < 8; ++d) { const int j = pos0 + d; if (d >= -half && d < half && j >= 0 && j < S) { const u32x4 w = *(const u32x4*)(zs + (size_t)j * 512); POOL_ACC(w, +); } }
.Lpool_first:
	s_lshl_b32 s25, s3, 10
	s_add_u32 s28, s80, s25
	s_addc_u32 s29, s81, 0
	s_add_u32 s28, s28, 0x199fe000
	s_addc_u32 s29, s29, 0
	s_lshl_b32 s25, s3, 11
	s_add_u32 s30, s80, s25
	s_addc_u32 s31, s81, 0
	s_add_u32 s30, s30, 0x21a00400
	s_addc_u32 s31, s31, 0
	s_mov_b64 s[40:41], s[28:29]
	s_add_u32 s40, s40, 0x2000
	s_addc_u32 s41, s41, 0
	global_load_dwordx4 v[160:163], v0, s[40:41]
	global_load_dwordx4 v[168:171], v0, s[40:41] offset:1024
	global_load_dwordx4 v[172:175], v0, s[40:41] offset:2048
	global_load_dwordx4 v[180:183], v0, s[40:41] offset:3072
	s_add_u32 s40, s40, 0x1000
	s_addc_u32 s41, s41, 0
	global_load_dwordx4 v[184:187], v0, s[40:41]
	global_load_dwordx4 v[188:191], v0, s[40:41] offset:1024
	global_load_dwordx4 v[246:249], v0, s[40:41] offset:2048
	global_load_dwordx4 v[250:253], v0, s[40:41] offset:3072
	s_add_u32 s40, s40, 0x1000
	s_addc_u32 s41, s41, 0
	v_lshlrev_b32_e32 v4, 10, v26
	v_add_u32_e32 v237, 0x2000, v0
	v_add_u32_e32 v36, v237, v4
	v_sub_u32_e32 v37, v237, v4
	v_ffbl_b32_e32 v6, v26
	v_sub_u32_e32 v6, 0x7e, v6
	v_lshlrev_b32_e32 v228, 23, v6
	v_mov_b32_e32 v8, 0
	v_mov_b32_e32 v9, 0
	v_mov_b32_e32 v10, 0
	v_mov_b32_e32 v11, 0
	v_mov_b32_e32 v12, 0
	v_mov_b32_e32 v13, 0
	v_mov_b32_e32 v14, 0
	v_mov_b32_e32 v15, 0
	s_waitcnt vmcnt(7)
	v_lshlrev_b32_e32 v4, 16, v160
	v_and_b32_e32 v6, 0xffff0000, v160
	v_lshlrev_b32_e32 v7, 16, v161
	v_and_b32_e32 v24, 0xffff0000, v161
	v_lshlrev_b32_e32 v25, 16, v162
	v_and_b32_e32 v164, 0xffff0000, v162
	v_lshlrev_b32_e32 v165, 16, v163
	v_and_b32_e32 v192, 0xffff0000, v163
	v_add_f32_e32 v8, v8, v4
	v_add_f32_e32 v9, v9, v6
	v_add_f32_e32 v10, v10, v7
	v_add_f32_e32 v11, v11, v24
	v_add_f32_e32 v12, v12, v25
	v_add_f32_e32 v13, v13, v164
	v_add_f32_e32 v14, v14, v165
	v_add_f32_e32 v15, v15, v192
	s_waitcnt vmcnt(6)
	s_mov_b32 exec_lo, 0xffff0000
	s_mov_b32 exec_hi, 0xffffffff
	v_lshlrev_b32_e32 v4, 16, v168
	v_and_b32_e32 v6, 0xffff0000, v168
	v_lshlrev_b32_e32 v7, 16, v169
	v_and_b32_e32 v24, 0xffff0000, v169
	v_lshlrev_b32_e32 v25, 16, v170
	v_and_b32_e32 v164, 0xffff0000, v170
	v_lshlrev_b32_e32 v165, 16, v171
	v_and_b32_e32 v192, 0xffff0000, v171
	v_add_f32_e32 v8, v8, v4
	v_add_f32_e32 v9, v9, v6
	v_add_f32_e32 v10, v10, v7
	v_add_f32_e32 v11, v11, v24
	v_add_f32_e32 v12, v12, v25
	v_add_f32_e32 v13, v13, v164
	v_add_f32_e32 v14, v14, v165
	v_add_f32_e32 v15, v15, v192
	s_waitcnt vmcnt(5)
	s_mov_b32 exec_lo, 0
	s_mov_b32 exec_hi, 0xffffffff
	v_lshlrev_b32_e32 v4, 16, v172
	v_and_b32_e32 v6, 0xffff0000, v172
	v_lshlrev_b32_e32 v7, 16, v173
	v_and_b32_e32 v24, 0xffff0000, v173
	v_lshlrev_b32_e32 v25, 16, v174
	v_and_b32_e32 v164, 0xffff0000, v174
	v_lshlrev_b32_e32 v165, 16, v175
	v_and_b32_e32 v192, 0xffff0000, v175
	v_add_f32_e32 v8, v8, v4
	v_add_f32_e32 v9, v9, v6
	v_add_f32_e32 v10, v10, v7
	v_add_f32_e32 v11, v11, v24
	v_add_f32_e32 v12, v12, v25
	v_add_f32_e32 v13, v13, v164
	v_add_f32_e32 v14, v14, v165
	v_add_f32_e32 v15, v15, v192
	s_waitcnt vmcnt(4)
	v_lshlrev_b32_e32 v4, 16, v180
	v_and_b32_e32 v6, 0xffff0000, v180
	v_lshlrev_b32_e32 v7, 16, v181
	v_and_b32_e32 v24, 0xffff0000, v181
	v_lshlrev_b32_e32 v25, 16, v182
	v_and_b32_e32 v164, 0xffff0000, v182
	v_lshlrev_b32_e32 v165, 16, v183
	v_and_b32_e32 v192, 0xffff0000, v183
	v_add_f32_e32 v8, v8, v4
	v_add_f32_e32 v9, v9, v6
	v_add_f32_e32 v10, v10, v7
	v_add_f32_e32 v11, v11, v24
	v_add_f32_e32 v12, v12, v25
	v_add_f32_e32 v13, v13, v164
	v_add_f32_e32 v14, v14, v165
	v_add_f32_e32 v15, v15, v192
	s_waitcnt vmcnt(3)
	s_mov_b32 exec_lo, 0
	s_mov_b32 exec_hi, 0xffff0000
	v_lshlrev_b32_e32 v4, 16, v184
	v_and_b32_e32 v6, 0xffff0000, v184
	v_lshlrev_b32_e32 v7, 16, v185
	v_and_b32_e32 v24, 0xffff0000, v185
	v_lshlrev_b32_e32 v25, 16, v186
	v_and_b32_e32 v164, 0xffff0000, v186
	v_lshlrev_b32_e32 v165, 16, v187
	v_and_b32_e32 v192, 0xffff0000, v187
	v_add_f32_e32 v8, v8, v4
	v_add_f32_e32 v9, v9, v6
	v_add_f32_e32 v10, v10, v7
	v_add_f32_e32 v11, v11, v24
	v_add_f32_e32 v12, v12, v25
	v_add_f32_e32 v13, v13, v164
	v_add_f32_e32 v14, v14, v165
	v_add_f32_e32 v15, v15, v192
	s_waitcnt vmcnt(2)
	v_lshlrev_b32_e32 v4, 16, v188
	v_and_b32_e32 v6, 0xffff0000, v188
	v_lshlrev_b32_e32 v7, 16, v189
	v_and_b32_e32 v24, 0xffff0000, v189
	v_lshlrev_b32_e32 v25, 16, v190
	v_and_b32_e32 v164, 0xffff0000, v190
	v_lshlrev_b32_e32 v165, 16, v191
	v_and_b32_e32 v192, 0xffff0000, v191
	v_add_f32_e32 v8, v8, v4
	v_add_f32_e32 v9, v9, v6
	v_add_f32_e32 v10, v10, v7
	v_add_f32_e32 v11, v11, v24
	v_add_f32_e32 v12, v12, v25
	v_add_f32_e32 v13, v13, v164
	v_add_f32_e32 v14, v14, v165
	v_add_f32_e32 v15, v15, v192
	s_waitcnt vmcnt(1)
	v_lshlrev_b32_e32 v4, 16, v246
	v_and_b32_e32 v6, 0xffff0000, v246
	v_lshlrev_b32_e32 v7, 16, v247
	v_and_b32_e32 v24, 0xffff0000, v247
	v_lshlrev_b32_e32 v25, 16, v248
	v_and_b32_e32 v164, 0xffff0000, v248
	v_lshlrev_b32_e32 v165, 16, v249
	v_and_b32_e32 v192, 0xffff0000, v249
	v_add_f32_e32 v8, v8, v4
	v_add_f32_e32 v9, v9, v6
	v_add_f32_e32 v10, v10, v7
	v_add_f32_e32 v11, v11, v24
	v_add_f32_e32 v12, v12, v25
	v_add_f32_e32 v13, v13, v164
	v_add_f32_e32 v14, v14, v165
	v_add_f32_e32 v15, v15, v192
	s_waitcnt vmcnt(0)
; __device__ __forceinline__ unsigned cvt_pk_bf16(float lo, float hi) { unsigned r; asm volatile("v_cvt_pk_bf16_f32 %0, %1, %2" : "=v"(r) : "v"(lo), "v"(hi)); return r; }
; __device__ __forceinline__ float bflo(unsigned w) { return __uint_as_float(w << 16); }
; __device__ __forceinline__ float bfhi(unsigned w) { return __uint_as_float(w & 0xffff0000u); }
; #define POOL_ACC(V_, sg) do { s0 += sg bflo(V_.x); s1 += sg bfhi(V_.x); s2 += sg bflo(V_.y); s3 += sg bfhi(V_.y); s4 += sg bflo(V_.z); s5 += sg bfhi(V_.z); s6 += sg bflo(V_.w); s7 += sg bfhi(V_.w); } while (0)
; __device__ __forceinline__ void pool_phase(const bf16_t* zp, bf16_t* mixed, const int wave_s) {
;     ...
;         for (int i = 0; i < 64; ++i) {
;             const int sp = pos0 + i, lo = max(sp - half, 0), hi = min(sp + half - 1, S - 1);
;             const float ic = 1.0f / (float)(hi - lo + 1);
;             const u32x4 w = *(const u32x4*)(zs + (size_t)sp * 512);
;             u32x4 o;
;             o.x = cvt_pk_bf16(s0 * ic - bflo(w.x), s1 * ic - bfhi(w.x)); o.y = cvt_pk_bf16(s2 * ic - bflo(w.y), s3 * ic - bfhi(w.y));
;             o.z = cvt_pk_bf16(s4 * ic - bflo(w.z), s5 * ic - bfhi(w.z)); o.w = cvt_pk_bf16(s6 * ic - bflo(w.w), s7 * ic - bfhi(w.w));
;             *(u32x4*)(ms + (size_t)sp * DM) = o;
;             const int jn = sp + half, jo = sp - half;
;             if (jn < S) { const u32x4 wn = *(const u32x4*)(zs + (size_t)jn * 512); POOL_ACC(wn, +); }
;             if (jo >= 0) { const u32x4 wo = *(const u32x4*)(zs + (size_t)jo * 512); POOL_ACC(wo, -); }
	v_lshlrev_b32_e32 v4, 16, v250
	v_and_b32_e32 v6, 0xffff0000, v250
	v_lshlrev_b32_e32 v7, 16, v251
	v_and_b32_e32 v24, 0xffff0000, v251
	v_lshlrev_b32_e32 v25, 16, v252
	v_and_b32_e32 v164, 0xffff0000, v252
	v_lshlrev_b32_e32 v165, 16, v253
	v_and_b32_e32 v192, 0xffff0000, v253
	v_add_f32_e32 v8, v8, v4
	v_add_f32_e32 v9, v9, v6
	v_add_f32_e32 v10, v10, v7
	v_add_f32_e32 v11, v11, v24
	v_add_f32_e32 v12, v12, v25
	v_add_f32_e32 v13, v13, v164
	v_add_f32_e32 v14, v14, v165
	v_add_f32_e32 v15, v15, v192
	s_mov_b32 exec_lo, 0xffffffff
	s_mov_b32 exec_hi, 0xffffffff
	global_load_dwordx4 v[160:163], v237, s[28:29]
	global_load_dwordx4 v[168:171], v36, s[28:29]
	global_load_dwordx4 v[172:175], v37, s[28:29]
	global_load_dwordx4 v[180:183], v237, s[28:29] offset:1024
	global_load_dwordx4 v[184:187], v36, s[28:29] offset:1024
	global_load_dwordx4 v[188:191], v37, s[28:29] offset:1024
	global_load_dwordx4 v[246:249], v237, s[28:29] offset:2048
	global_load_dwordx4 v[250:253], v36, s[28:29] offset:2048
	global_load_dwordx4 v[20:23], v37, s[28:29] offset:2048
	global_load_dwordx4 v[28:31], v237, s[28:29] offset:3072
	global_load_dwordx4 v[32:35], v36, s[28:29] offset:3072
	global_load_dwordx4 v[16:19], v37, s[28:29] offset:3072
	s_add_u32 s28, s28, 0x1000
	s_addc_u32 s29, s29, 0
	s_waitcnt vmcnt(9)
	v_add_u32_e32 v228, 0, v26
	v_lshlrev_b32_e32 v164, 1, v26
	v_min_u32_e32 v228, v228, v164
	v_cvt_f32_u32_e32 v228, v228
	v_div_scale_f32 v4, s[2:3], v228, v228, 1.0
	v_rcp_f32_e32 v6, v4
	v_div_scale_f32 v7, vcc, 1.0, v228, 1.0
	v_fma_f32 v24, -v4, v6, 1.0
	v_fmac_f32_e32 v6, v24, v6
	v_mul_f32_e32 v24, v7, v6
	v_fma_f32 v25, -v4, v24, v7
	v_fmac_f32_e32 v24, v25, v6
	v_fma_f32 v4, -v4, v24, v7
	v_div_fmas_f32 v6, v4, v6, v24
	v_div_fixup_f32 v228, v6, v228, 1.0
	v_lshlrev_b32_e32 v4, 16, v160
	v_and_b32_e32 v6, 0xffff0000, v160
	v_lshlrev_b32_e32 v7, 16, v161
	v_and_b32_e32 v24, 0xffff0000, v161
	v_lshlrev_b32_e32 v25, 16, v162
	v_and_b32_e32 v164, 0xffff0000, v162
	v_lshlrev_b32_e32 v165, 16, v163
	v_and_b32_e32 v192, 0xffff0000, v163
	v_fma_f32 v4, v8, v228, -v4
	v_fma_f32 v6, v9, v228, -v6
	v_fma_f32 v7, v10, v228, -v7
	v_fma_f32 v24, v11, v228, -v24
	v_fma_f32 v25, v12, v228, -v25
	v_fma_f32 v164, v13, v228, -v164
	v_fma_f32 v165, v14, v228, -v165
	v_fma_f32 v192, v15, v228, -v192
	v_cvt_pk_bf16_f32 v160, v4, v6
	v_cvt_pk_bf16_f32 v161, v7, v24
	v_cvt_pk_bf16_f32 v162, v25, v164
	v_cvt_pk_bf16_f32 v163, v165, v192
	global_store_dwordx4 v0, v[160:163], s[30:31]
	v_lshlrev_b32_e32 v4, 16, v168
	v_and_b32_e32 v6, 0xffff0000, v168
	v_lshlrev_b32_e32 v7, 16, v169
	v_and_b32_e32 v24, 0xffff0000, v169
	v_lshlrev_b32_e32 v25, 16, v170
	v_and_b32_e32 v164, 0xffff0000, v170
	v_lshlrev_b32_e32 v165, 16, v171
	v_and_b32_e32 v192, 0xffff0000, v171
	v_add_f32_e32 v8, v8, v4
	v_add_f32_e32 v9, v9, v6
	v_add_f32_e32 v10, v10, v7
	v_add_f32_e32 v11, v11, v24
	v_add_f32_e32 v12, v12, v25
	v_add_f32_e32 v13, v13, v164
	v_add_f32_e32 v14, v14, v165
	v_add_f32_e32 v15, v15, v192
	global_load_dwordx4 v[160:163], v237, s[28:29]
	global_load_dwordx4 v[168:171], v36, s[28:29]
	global_load_dwordx4 v[172:175], v37, s[28:29]
	s_waitcnt vmcnt(9)
	v_add_u32_e32 v228, 1, v26
	v_lshlrev_b32_e32 v164, 1, v26
	v_min_u32_e32 v228, v228, v164
	v_cvt_f32_u32_e32 v228, v228
	v_div_scale_f32 v4, s[2:3], v228, v228, 1.0
	v_rcp_f32_e32 v6, v4
	v_div_scale_f32 v7, vcc, 1.0, v228, 1.0
	v_fma_f32 v24, -v4, v6, 1.0
	v_fmac_f32_e32 v6, v24, v6
	v_mul_f32_e32 v24, v7, v6
	v_fma_f32 v25, -v4, v24, v7
	v_fmac_f32_e32 v24, v25, v6
	v_fma_f32 v4, -v4, v24, v7
	v_div_fmas_f32 v6, v4, v6, v24
	v_div_fixup_f32 v228, v6, v228, 1.0
	v_lshlrev_b32_e32 v4, 16, v180
	v_and_b32_e32 v6, 0xffff0000, v180
	v_lshlrev_b32_e32 v7, 16, v181
	v_and_b32_e32 v24, 0xffff0000, v181
	v_lshlrev_b32_e32 v25, 16, v182
	v_and_b32_e32 v164, 0xffff0000, v182
	v_lshlrev_b32_e32 v165, 16, v183
	v_and_b32_e32 v192, 0xffff0000, v183
	v_fma_f32 v4, v8, v228, -v4
	v_fma_f32 v6, v9, v228, -v6
	v_fma_f32 v7, v10, v228, -v7
	v_fma_f32 v24, v11, v228, -v24
	v_fma_f32 v25, v12, v228, -v25
	v_fma_f32 v164, v13, v228, -v164
	v_fma_f32 v165, v14, v228, -v165
	v_fma_f32 v192, v15, v228, -v192
	v_cvt_pk_bf16_f32 v180, v4, v6
	v_cvt_pk_bf16_f32 v181, v7, v24
	v_cvt_pk_bf16_f32 v182, v25, v164
	v_cvt_pk_bf16_f32 v183, v165, v192
	global_store_dwordx4 v0, v[180:183], s[30:31] offset:2048
	s_add_u32 s30, s30, 0x1000
	s_addc_u32 s31, s31, 0
	v_lshlrev_b32_e32 v4, 16, v184
	v_and_b32_e32 v6, 0xffff0000, v184
	v_lshlrev_b32_e32 v7, 16, v185
	v_and_b32_e32 v24, 0xffff0000, v185
	v_lshlrev_b32_e32 v25, 16, v186
	v_and_b32_e32 v164, 0xffff0000, v186
	v_lshlrev_b32_e32 v165, 16, v187
	v_and_b32_e32 v192, 0xffff0000, v187
	v_add_f32_e32 v8, v8, v4
	v_add_f32_e32 v9, v9, v6
	v_add_f32_e32 v10, v10, v7
	v_add_f32_e32 v11, v11, v24
	v_add_f32_e32 v12, v12, v25
	v_add_f32_e32 v13, v13, v164
	v_add_f32_e32 v14, v14, v165
	v_add_f32_e32 v15, v15, v192
	s_mov_b32 exec_lo, 0xffff
	s_mov_b32 exec_hi, 0x0
	v_lshlrev_b32_e32 v4, 16, v188
	v_and_b32_e32 v6, 0xffff0000, v188
	v_lshlrev_b32_e32 v7, 16, v189
	v_and_b32_e32 v24, 0xffff0000, v189
	v_lshlrev_b32_e32 v25, 16, v190
	v_and_b32_e32 v164, 0xffff0000, v190
	v_lshlrev_b32_e32 v165, 16, v191
	v_and_b32_e32 v192, 0xffff0000, v191
	v_sub_f32_e32 v8, v8, v4
	v_sub_f32_e32 v9, v9, v6
	v_sub_f32_e32 v10, v10, v7
	v_sub_f32_e32 v11, v11, v24
	v_sub_f32_e32 v12, v12, v25
	v_sub_f32_e32 v13, v13, v164
	v_sub_f32_e32 v14, v14, v165
	v_sub_f32_e32 v15, v15, v192
	s_mov_b32 exec_lo, -1
	s_mov_b32 exec_hi, -1
	global_load_dwordx4 v[180:183], v237, s[28:29] offset:1024
	global_load_dwordx4 v[184:187], v36, s[28:29] offset:1024
	global_load_dwordx4 v[188:191], v37, s[28:29] offset:1024
	s_waitcnt vmcnt(9)
; __device__ __forceinline__ unsigned cvt_pk_bf16(float lo, float hi) { unsigned r; asm volatile("v_cvt_pk_bf16_f32 %0, %1, %2" : "=v"(r) : "v"(lo), "v"(hi)); return r; }
; __device__ __forceinline__ float bflo(unsigned w) { return __uint_as_float(w << 16); }
; __device__ __forceinline__ float bfhi(unsigned w) { return __uint_as_float(w & 0xffff0000u); }
; #define POOL_ACC(V_, sg) do { s0 += sg bflo(V_.x); s1 += sg bfhi(V_.x); s2 += sg bflo(V_.y); s3 += sg bfhi(V_.y); s4 += sg bflo(V_.z); s5 += sg bfhi(V_.z); s6 += sg bflo(V_.w); s7 += sg bfhi(V_.w); } while (0)
; __device__ __forceinline__ void pool_phase(const bf16_t* zp, bf16_t* mixed, const int wave_s) {
;     ...
;         for (int i = 0; i < 64; ++i) {
;             const int sp = pos0 + i, lo = max(sp - half, 0), hi = min(sp + half - 1, S - 1);
;             const float ic = 1.0f / (float)(hi - lo + 1);
;             const u32x4 w = *(const u32x4*)(zs + (size_t)sp * 512);
;             u32x4 o;
;             o.x = cvt_pk_bf16(s0 * ic - bflo(w.x), s1 * ic - bfhi(w.x)); o.y = cvt_pk_bf16(s2 * ic - bflo(w.y), s3 * ic - bfhi(w.y));
;             o.z = cvt_pk_bf16(s4 * ic - bflo(w.z), s5 * ic - bfhi(w.z)); o.w = cvt_pk_bf16(s6 * ic - bflo(w.w), s7 * ic - bfhi(w.w));
;             *(u32x4*)(ms + (size_t)sp * DM) = o;
;             const int jn = sp + half, jo = sp - half;
;             if (jn < S) { const u32x4 wn = *(const u32x4*)(zs + (size_t)jn * 512); POOL_ACC(wn, +); }
;             if (jo >= 0) { const u32x4 wo = *(const u32x4*)(zs + (size_t)jo * 512); POOL_ACC(wo, -); }
	v_add_u32_e32 v228, 2, v26
	v_lshlrev_b32_e32 v164, 1, v26
	v_min_u32_e32 v228, v228, v164
	v_cvt_f32_u32_e32 v228, v228
	v_div_scale_f32 v4, s[2:3], v228, v228, 1.0
	v_rcp_f32_e32 v6, v4
	v_div_scale_f32 v7, vcc, 1.0, v228, 1.0
	v_fma_f32 v24, -v4, v6, 1.0
	v_fmac_f32_e32 v6, v24, v6
	v_mul_f32_e32 v24, v7, v6
	v_fma_f32 v25, -v4, v24, v7
	v_fmac_f32_e32 v24, v25, v6
	v_fma_f32 v4, -v4, v24, v7
	v_div_fmas_f32 v6, v4, v6, v24
	v_div_fixup_f32 v228, v6, v228, 1.0
	v_lshlrev_b32_e32 v4, 16, v246
	v_and_b32_e32 v6, 0xffff0000, v246
	v_lshlrev_b32_e32 v7, 16, v247
	v_and_b32_e32 v24, 0xffff0000, v247
	v_lshlrev_b32_e32 v25, 16, v248
	v_and_b32_e32 v164, 0xffff0000, v248
	v_lshlrev_b32_e32 v165, 16, v249
	v_and_b32_e32 v192, 0xffff0000, v249
	v_fma_f32 v4, v8, v228, -v4
	v_fma_f32 v6, v9, v228, -v6
	v_fma_f32 v7, v10, v228, -v7
	v_fma_f32 v24, v11, v228, -v24
	v_fma_f32 v25, v12, v228, -v25
	v_fma_f32 v164, v13, v228, -v164
	v_fma_f32 v165, v14, v228, -v165
	v_fma_f32 v192, v15, v228, -v192
	v_cvt_pk_bf16_f32 v246, v4, v6
	v_cvt_pk_bf16_f32 v247, v7, v24
	v_cvt_pk_bf16_f32 v248, v25, v164
	v_cvt_pk_bf16_f32 v249, v165, v192
	global_store_dwordx4 v0, v[246:249], s[30:31]
	v_lshlrev_b32_e32 v4, 16, v250
	v_and_b32_e32 v6, 0xffff0000, v250
	v_lshlrev_b32_e32 v7, 16, v251
	v_and_b32_e32 v24, 0xffff0000, v251
	v_lshlrev_b32_e32 v25, 16, v252
	v_and_b32_e32 v164, 0xffff0000, v252
	v_lshlrev_b32_e32 v165, 16, v253
	v_and_b32_e32 v192, 0xffff0000, v253
	v_add_f32_e32 v8, v8, v4
	v_add_f32_e32 v9, v9, v6
	v_add_f32_e32 v10, v10, v7
	v_add_f32_e32 v11, v11, v24
	v_add_f32_e32 v12, v12, v25
	v_add_f32_e32 v13, v13, v164
	v_add_f32_e32 v14, v14, v165
	v_add_f32_e32 v15, v15, v192
	s_mov_b32 exec_lo, 0xffffffff
	s_mov_b32 exec_hi, 0x0
	v_lshlrev_b32_e32 v4, 16, v20
	v_and_b32_e32 v6, 0xffff0000, v20
	v_lshlrev_b32_e32 v7, 16, v21
	v_and_b32_e32 v24, 0xffff0000, v21
	v_lshlrev_b32_e32 v25, 16, v22
	v_and_b32_e32 v164, 0xffff0000, v22
	v_lshlrev_b32_e32 v165, 16, v23
	v_and_b32_e32 v192, 0xffff0000, v23
	v_sub_f32_e32 v8, v8, v4
	v_sub_f32_e32 v9, v9, v6
	v_sub_f32_e32 v10, v10, v7
	v_sub_f32_e32 v11, v11, v24
	v_sub_f32_e32 v12, v12, v25
	v_sub_f32_e32 v13, v13, v164
	v_sub_f32_e32 v14, v14, v165
	v_sub_f32_e32 v15, v15, v192
	s_mov_b32 exec_lo, -1
	s_mov_b32 exec_hi, -1
	global_load_dwordx4 v[246:249], v237, s[28:29] offset:2048
	global_load_dwordx4 v[250:253], v36, s[28:29] offset:2048
	global_load_dwordx4 v[20:23], v37, s[28:29] offset:2048
	s_waitcnt vmcnt(9)
	v_add_u32_e32 v228, 3, v26
	v_lshlrev_b32_e32 v164, 1, v26
	v_min_u32_e32 v228, v228, v164
	v_cvt_f32_u32_e32 v228, v228
	v_div_scale_f32 v4, s[2:3], v228, v228, 1.0
	v_rcp_f32_e32 v6, v4
	v_div_scale_f32 v7, vcc, 1.0, v228, 1.0
	v_fma_f32 v24, -v4, v6, 1.0
	v_fmac_f32_e32 v6, v24, v6
	v_mul_f32_e32 v24, v7, v6
	v_fma_f32 v25, -v4, v24, v7
	v_fmac_f32_e32 v24, v25, v6
	v_fma_f32 v4, -v4, v24, v7
	v_div_fmas_f32 v6, v4, v6, v24
	v_div_fixup_f32 v228, v6, v228, 1.0
	v_lshlrev_b32_e32 v4, 16, v28
	v_and_b32_e32 v6, 0xffff0000, v28
	v_lshlrev_b32_e32 v7, 16, v29
	v_and_b32_e32 v24, 0xffff0000, v29
	v_lshlrev_b32_e32 v25, 16, v30
	v_and_b32_e32 v164, 0xffff0000, v30
	v_lshlrev_b32_e32 v165, 16, v31
	v_and_b32_e32 v192, 0xffff0000, v31
	v_fma_f32 v4, v8, v228, -v4
	v_fma_f32 v6, v9, v228, -v6
	v_fma_f32 v7, v10, v228, -v7
	v_fma_f32 v24, v11, v228, -v24
	v_fma_f32 v25, v12, v228, -v25
	v_fma_f32 v164, v13, v228, -v164
	v_fma_f32 v165, v14, v228, -v165
	v_fma_f32 v192, v15, v228, -v192
	v_cvt_pk_bf16_f32 v28, v4, v6
	v_cvt_pk_bf16_f32 v29, v7, v24
	v_cvt_pk_bf16_f32 v30, v25, v164
	v_cvt_pk_bf16_f32 v31, v165, v192
	global_store_dwordx4 v0, v[28:31], s[30:31] offset:2048
	s_add_u32 s30, s30, 0x1000
	s_addc_u32 s31, s31, 0
	v_lshlrev_b32_e32 v4, 16, v32
	v_and_b32_e32 v6, 0xffff0000, v32
	v_lshlrev_b32_e32 v7, 16, v33
	v_and_b32_e32 v24, 0xffff0000, v33
	v_lshlrev_b32_e32 v25, 16, v34
	v_and_b32_e32 v164, 0xffff0000, v34
	v_lshlrev_b32_e32 v165, 16, v35
	v_and_b32_e32 v192, 0xffff0000, v35
	v_add_f32_e32 v8, v8, v4
	v_add_f32_e32 v9, v9, v6
	v_add_f32_e32 v10, v10, v7
	v_add_f32_e32 v11, v11, v24
	v_add_f32_e32 v12, v12, v25
	v_add_f32_e32 v13, v13, v164
	v_add_f32_e32 v14, v14, v165
	v_add_f32_e32 v15, v15, v192
	s_mov_b32 exec_lo, 0xffffffff
	s_mov_b32 exec_hi, 0x0
	v_lshlrev_b32_e32 v4, 16, v16
	v_and_b32_e32 v6, 0xffff0000, v16
	v_lshlrev_b32_e32 v7, 16, v17
	v_and_b32_e32 v24, 0xffff0000, v17
	v_lshlrev_b32_e32 v25, 16, v18
	v_and_b32_e32 v164, 0xffff0000, v18
	v_lshlrev_b32_e32 v165, 16, v19
	v_and_b32_e32 v192, 0xffff0000, v19
	v_sub_f32_e32 v8, v8, v4
	v_sub_f32_e32 v9, v9, v6
	v_sub_f32_e32 v10, v10, v7
	v_sub_f32_e32 v11, v11, v24
	v_sub_f32_e32 v12, v12, v25
	v_sub_f32_e32 v13, v13, v164
	v_sub_f32_e32 v14, v14, v165
	v_sub_f32_e32 v15, v15, v192
	s_mov_b32 exec_lo, -1
	s_mov_b32 exec_hi, -1
	global_load_dwordx4 v[28:31], v237, s[28:29] offset:3072
	global_load_dwordx4 v[32:35], v36, s[28:29] offset:3072
	global_load_dwordx4 v[16:19], v37, s[28:29] offset:3072
	s_add_u32 s28, s28, 0x1000
	s_addc_u32 s29, s29, 0
	s_waitcnt vmcnt(9)
; __device__ __forceinline__ unsigned cvt_pk_bf16(float lo, float hi) { unsigned r; asm volatile("v_cvt_pk_bf16_f32 %0, %1, %2" : "=v"(r) : "v"(lo), "v"(hi)); return r; }
; __device__ __forceinline__ float bflo(unsigned w) { return __uint_as_float(w << 16); }
; __device__ __forceinline__ float bfhi(unsigned w) { return __uint_as_float(w & 0xffff0000u); }
; #define POOL_ACC(V_, sg) do { s0 += sg bflo(V_.x); s1 += sg bfhi(V_.x); s2 += sg bflo(V_.y); s3 += sg bfhi(V_.y); s4 += sg bflo(V_.z); s5 += sg bfhi(V_.z); s6 += sg bflo(V_.w); s7 += sg bfhi(V_.w); } while (0)
; __device__ __forceinline__ void pool_phase(const bf16_t* zp, bf16_t* mixed, const int wave_s) {
;     ...
;         for (int i = 0; i < 64; ++i) {
;             const int sp = pos0 + i, lo = max(sp - half, 0), hi = min(sp + half - 1, S - 1);
;             const float ic = 1.0f / (float)(hi - lo + 1);
;             const u32x4 w = *(const u32x4*)(zs + (size_t)sp * 512);
;             u32x4 o;
;             o.x = cvt_pk_bf16(s0 * ic - bflo(w.x), s1 * ic - bfhi(w.x)); o.y = cvt_pk_bf16(s2 * ic - bflo(w.y), s3 * ic - bfhi(w.y));
;             o.z = cvt_pk_bf16(s4 * ic - bflo(w.z), s5 * ic - bfhi(w.z)); o.w = cvt_pk_bf16(s6 * ic - bflo(w.w), s7 * ic - bfhi(w.w));
;             *(u32x4*)(ms + (size_t)sp * DM) = o;
;             const int jn = sp + half, jo = sp - half;
;             if (jn < S) { const u32x4 wn = *(const u32x4*)(zs + (size_t)jn * 512); POOL_ACC(wn, +); }
;             if (jo >= 0) { const u32x4 wo = *(const u32x4*)(zs + (size_t)jo * 512); POOL_ACC(wo, -); }
	v_add_u32_e32 v228, 4, v26
	v_lshlrev_b32_e32 v164, 1, v26
	v_min_u32_e32 v228, v228, v164
	v_cvt_f32_u32_e32 v228, v228
	v_div_scale_f32 v4, s[2:3], v228, v228, 1.0
	v_rcp_f32_e32 v6, v4
	v_div_scale_f32 v7, vcc, 1.0, v228, 1.0
	v_fma_f32 v24, -v4, v6, 1.0
	v_fmac_f32_e32 v6, v24, v6
	v_mul_f32_e32 v24, v7, v6
	v_fma_f32 v25, -v4, v24, v7
	v_fmac_f32_e32 v24, v25, v6
	v_fma_f32 v4, -v4, v24, v7
	v_div_fmas_f32 v6, v4, v6, v24
	v_div_fixup_f32 v228, v6, v228, 1.0
	v_lshlrev_b32_e32 v4, 16, v160
	v_and_b32_e32 v6, 0xffff0000, v160
	v_lshlrev_b32_e32 v7, 16, v161
	v_and_b32_e32 v24, 0xffff0000, v161
	v_lshlrev_b32_e32 v25, 16, v162
	v_and_b32_e32 v164, 0xffff0000, v162
	v_lshlrev_b32_e32 v165, 16, v163
	v_and_b32_e32 v192, 0xffff0000, v163
	v_fma_f32 v4, v8, v228, -v4
	v_fma_f32 v6, v9, v228, -v6
	v_fma_f32 v7, v10, v228, -v7
	v_fma_f32 v24, v11, v228, -v24
	v_fma_f32 v25, v12, v228, -v25
	v_fma_f32 v164, v13, v228, -v164
	v_fma_f32 v165, v14, v228, -v165
	v_fma_f32 v192, v15, v228, -v192
	v_cvt_pk_bf16_f32 v160, v4, v6
	v_cvt_pk_bf16_f32 v161, v7, v24
	v_cvt_pk_bf16_f32 v162, v25, v164
	v_cvt_pk_bf16_f32 v163, v165, v192
	global_store_dwordx4 v0, v[160:163], s[30:31]
	v_lshlrev_b32_e32 v4, 16, v168
	v_and_b32_e32 v6, 0xffff0000, v168
	v_lshlrev_b32_e32 v7, 16, v169
	v_and_b32_e32 v24, 0xffff0000, v169
	v_lshlrev_b32_e32 v25, 16, v170
	v_and_b32_e32 v164, 0xffff0000, v170
	v_lshlrev_b32_e32 v165, 16, v171
	v_and_b32_e32 v192, 0xffff0000, v171
	v_add_f32_e32 v8, v8, v4
	v_add_f32_e32 v9, v9, v6
	v_add_f32_e32 v10, v10, v7
	v_add_f32_e32 v11, v11, v24
	v_add_f32_e32 v12, v12, v25
	v_add_f32_e32 v13, v13, v164
	v_add_f32_e32 v14, v14, v165
	v_add_f32_e32 v15, v15, v192
	s_mov_b32 exec_lo, 0xffffffff
	s_mov_b32 exec_hi, 0xffff
	v_lshlrev_b32_e32 v4, 16, v172
	v_and_b32_e32 v6, 0xffff0000, v172
	v_lshlrev_b32_e32 v7, 16, v173
	v_and_b32_e32 v24, 0xffff0000, v173
	v_lshlrev_b32_e32 v25, 16, v174
	v_and_b32_e32 v164, 0xffff0000, v174
	v_lshlrev_b32_e32 v165, 16, v175
	v_and_b32_e32 v192, 0xffff0000, v175
	v_sub_f32_e32 v8, v8, v4
	v_sub_f32_e32 v9, v9, v6
	v_sub_f32_e32 v10, v10, v7
	v_sub_f32_e32 v11, v11, v24
	v_sub_f32_e32 v12, v12, v25
	v_sub_f32_e32 v13, v13, v164
	v_sub_f32_e32 v14, v14, v165
	v_sub_f32_e32 v15, v15, v192
	s_mov_b32 exec_lo, -1
	s_mov_b32 exec_hi, -1
	global_load_dwordx4 v[160:163], v237, s[28:29]
	global_load_dwordx4 v[168:171], v36, s[28:29]
	global_load_dwordx4 v[172:175], v37, s[28:29]
	s_waitcnt vmcnt(9)
	v_add_u32_e32 v228, 5, v26
	v_lshlrev_b32_e32 v164, 1, v26
	v_min_u32_e32 v228, v228, v164
	v_cvt_f32_u32_e32 v228, v228
	v_div_scale_f32 v4, s[2:3], v228, v228, 1.0
	v_rcp_f32_e32 v6, v4
	v_div_scale_f32 v7, vcc, 1.0, v228, 1.0
	v_fma_f32 v24, -v4, v6, 1.0
	v_fmac_f32_e32 v6, v24, v6
	v_mul_f32_e32 v24, v7, v6
	v_fma_f32 v25, -v4, v24, v7
	v_fmac_f32_e32 v24, v25, v6
	v_fma_f32 v4, -v4, v24, v7
	v_div_fmas_f32 v6, v4, v6, v24
	v_div_fixup_f32 v228, v6, v228, 1.0
	v_lshlrev_b32_e32 v4, 16, v180
	v_and_b32_e32 v6, 0xffff0000, v180
	v_lshlrev_b32_e32 v7, 16, v181
	v_and_b32_e32 v24, 0xffff0000, v181
	v_lshlrev_b32_e32 v25, 16, v182
	v_and_b32_e32 v164, 0xffff0000, v182
	v_lshlrev_b32_e32 v165, 16, v183
	v_and_b32_e32 v192, 0xffff0000, v183
	v_fma_f32 v4, v8, v228, -v4
	v_fma_f32 v6, v9, v228, -v6
	v_fma_f32 v7, v10, v228, -v7
	v_fma_f32 v24, v11, v228, -v24
	v_fma_f32 v25, v12, v228, -v25
	v_fma_f32 v164, v13, v228, -v164
	v_fma_f32 v165, v14, v228, -v165
	v_fma_f32 v192, v15, v228, -v192
	v_cvt_pk_bf16_f32 v180, v4, v6
	v_cvt_pk_bf16_f32 v181, v7, v24
	v_cvt_pk_bf16_f32 v182, v25, v164
	v_cvt_pk_bf16_f32 v183, v165, v192
	global_store_dwordx4 v0, v[180:183], s[30:31] offset:2048
	s_add_u32 s30, s30, 0x1000
	s_addc_u32 s31, s31, 0
	v_lshlrev_b32_e32 v4, 16, v184
	v_and_b32_e32 v6, 0xffff0000, v184
	v_lshlrev_b32_e32 v7, 16, v185
	v_and_b32_e32 v24, 0xffff0000, v185
	v_lshlrev_b32_e32 v25, 16, v186
	v_and_b32_e32 v164, 0xffff0000, v186
	v_lshlrev_b32_e32 v165, 16, v187
	v_and_b32_e32 v192, 0xffff0000, v187
	v_add_f32_e32 v8, v8, v4
	v_add_f32_e32 v9, v9, v6
	v_add_f32_e32 v10, v10, v7
	v_add_f32_e32 v11, v11, v24
	v_add_f32_e32 v12, v12, v25
	v_add_f32_e32 v13, v13, v164
	v_add_f32_e32 v14, v14, v165
	v_add_f32_e32 v15, v15, v192
	s_mov_b32 exec_lo, 0xffffffff
	s_mov_b32 exec_hi, 0xffff
	v_lshlrev_b32_e32 v4, 16, v188
	v_and_b32_e32 v6, 0xffff0000, v188
	v_lshlrev_b32_e32 v7, 16, v189
	v_and_b32_e32 v24, 0xffff0000, v189
	v_lshlrev_b32_e32 v25, 16, v190
	v_and_b32_e32 v164, 0xffff0000, v190
	v_lshlrev_b32_e32 v165, 16, v191
	v_and_b32_e32 v192, 0xffff0000, v191
	v_sub_f32_e32 v8, v8, v4
	v_sub_f32_e32 v9, v9, v6
	v_sub_f32_e32 v10, v10, v7
	v_sub_f32_e32 v11, v11, v24
	v_sub_f32_e32 v12, v12, v25
	v_sub_f32_e32 v13, v13, v164
	v_sub_f32_e32 v14, v14, v165
	v_sub_f32_e32 v15, v15, v192
	s_mov_b32 exec_lo, -1
	s_mov_b32 exec_hi, -1
	global_load_dwordx4 v[180:183], v237, s[28:29] offset:1024
	global_load_dwordx4 v[184:187], v36, s[28:29] offset:1024
	global_load_dwordx4 v[188:191], v37, s[28:29] offset:1024
	s_waitcnt vmcnt(9)
; __device__ __forceinline__ unsigned cvt_pk_bf16(float lo, float hi) { unsigned r; asm volatile("v_cvt_pk_bf16_f32 %0, %1, %2" : "=v"(r) : "v"(lo), "v"(hi)); return r; }
; __device__ __forceinline__ float bflo(unsigned w) { return __uint_as_float(w << 16); }
; __device__ __forceinline__ float bfhi(unsigned w) { return __uint_as_float(w & 0xffff0000u); }
; #define POOL_ACC(V_, sg) do { s0 += sg bflo(V_.x); s1 += sg bfhi(V_.x); s2 += sg bflo(V_.y); s3 += sg bfhi(V_.y); s4 += sg bflo(V_.z); s5 += sg bfhi(V_.z); s6 += sg bflo(V_.w); s7 += sg bfhi(V_.w); } while (0)
; __device__ __forceinline__ void pool_phase(const bf16_t* zp, bf16_t* mixed, const int wave_s) {
;     ...
;         for (int i = 0; i < 64; ++i) {
;             const int sp = pos0 + i, lo = max(sp - half, 0), hi = min(sp + half - 1, S - 1);
;             const float ic = 1.0f / (float)(hi - lo + 1);
;             const u32x4 w = *(const u32x4*)(zs + (size_t)sp * 512);
;             u32x4 o;
;             o.x = cvt_pk_bf16(s0 * ic - bflo(w.x), s1 * ic - bfhi(w.x)); o.y = cvt_pk_bf16(s2 * ic - bflo(w.y), s3 * ic - bfhi(w.y));
;             o.z = cvt_pk_bf16(s4 * ic - bflo(w.z), s5 * ic - bfhi(w.z)); o.w = cvt_pk_bf16(s6 * ic - bflo(w.w), s7 * ic - bfhi(w.w));
;             *(u32x4*)(ms + (size_t)sp * DM) = o;
;             const int jn = sp + half, jo = sp - half;
;             if (jn < S) { const u32x4 wn = *(const u32x4*)(zs + (size_t)jn * 512); POOL_ACC(wn, +); }
;             if (jo >= 0) { const u32x4 wo = *(const u32x4*)(zs + (size_t)jo * 512); POOL_ACC(wo, -); }
	v_add_u32_e32 v228, 6, v26
	v_lshlrev_b32_e32 v164, 1, v26
	v_min_u32_e32 v228, v228, v164
	v_cvt_f32_u32_e32 v228, v228
	v_div_scale_f32 v4, s[2:3], v228, v228, 1.0
	v_rcp_f32_e32 v6, v4
	v_div_scale_f32 v7, vcc, 1.0, v228, 1.0
	v_fma_f32 v24, -v4, v6, 1.0
	v_fmac_f32_e32 v6, v24, v6
	v_mul_f32_e32 v24, v7, v6
	v_fma_f32 v25, -v4, v24, v7
	v_fmac_f32_e32 v24, v25, v6
	v_fma_f32 v4, -v4, v24, v7
	v_div_fmas_f32 v6, v4, v6, v24
	v_div_fixup_f32 v228, v6, v228, 1.0
	v_lshlrev_b32_e32 v4, 16, v246
	v_and_b32_e32 v6, 0xffff0000, v246
	v_lshlrev_b32_e32 v7, 16, v247
	v_and_b32_e32 v24, 0xffff0000, v247
	v_lshlrev_b32_e32 v25, 16, v248
	v_and_b32_e32 v164, 0xffff0000, v248
	v_lshlrev_b32_e32 v165, 16, v249
	v_and_b32_e32 v192, 0xffff0000, v249
	v_fma_f32 v4, v8, v228, -v4
	v_fma_f32 v6, v9, v228, -v6
	v_fma_f32 v7, v10, v228, -v7
	v_fma_f32 v24, v11, v228, -v24
	v_fma_f32 v25, v12, v228, -v25
	v_fma_f32 v164, v13, v228, -v164
	v_fma_f32 v165, v14, v228, -v165
	v_fma_f32 v192, v15, v228, -v192
	v_cvt_pk_bf16_f32 v246, v4, v6
	v_cvt_pk_bf16_f32 v247, v7, v24
	v_cvt_pk_bf16_f32 v248, v25, v164
	v_cvt_pk_bf16_f32 v249, v165, v192
	global_store_dwordx4 v0, v[246:249], s[30:31]
	v_lshlrev_b32_e32 v4, 16, v250
	v_and_b32_e32 v6, 0xffff0000, v250
	v_lshlrev_b32_e32 v7, 16, v251
	v_and_b32_e32 v24, 0xffff0000, v251
	v_lshlrev_b32_e32 v25, 16, v252
	v_and_b32_e32 v164, 0xffff0000, v252
	v_lshlrev_b32_e32 v165, 16, v253
	v_and_b32_e32 v192, 0xffff0000, v253
	v_add_f32_e32 v8, v8, v4
	v_add_f32_e32 v9, v9, v6
	v_add_f32_e32 v10, v10, v7
	v_add_f32_e32 v11, v11, v24
	v_add_f32_e32 v12, v12, v25
	v_add_f32_e32 v13, v13, v164
	v_add_f32_e32 v14, v14, v165
	v_add_f32_e32 v15, v15, v192
	s_mov_b32 exec_lo, 0xffffffff
	s_mov_b32 exec_hi, 0xffff
	v_lshlrev_b32_e32 v4, 16, v20
	v_and_b32_e32 v6, 0xffff0000, v20
	v_lshlrev_b32_e32 v7, 16, v21
	v_and_b32_e32 v24, 0xffff0000, v21
	v_lshlrev_b32_e32 v25, 16, v22
	v_and_b32_e32 v164, 0xffff0000, v22
	v_lshlrev_b32_e32 v165, 16, v23
	v_and_b32_e32 v192, 0xffff0000, v23
	v_sub_f32_e32 v8, v8, v4
	v_sub_f32_e32 v9, v9, v6
	v_sub_f32_e32 v10, v10, v7
	v_sub_f32_e32 v11, v11, v24
	v_sub_f32_e32 v12, v12, v25
	v_sub_f32_e32 v13, v13, v164
	v_sub_f32_e32 v14, v14, v165
	v_sub_f32_e32 v15, v15, v192
	s_mov_b32 exec_lo, -1
	s_mov_b32 exec_hi, -1
	global_load_dwordx4 v[246:249], v237, s[28:29] offset:2048
	global_load_dwordx4 v[250:253], v36, s[28:29] offset:2048
	global_load_dwordx4 v[20:23], v37, s[28:29] offset:2048
	s_waitcnt vmcnt(9)
	v_add_u32_e32 v228, 7, v26
	v_lshlrev_b32_e32 v164, 1, v26
	v_min_u32_e32 v228, v228, v164
	v_cvt_f32_u32_e32 v228, v228
	v_div_scale_f32 v4, s[2:3], v228, v228, 1.0
	v_rcp_f32_e32 v6, v4
	v_div_scale_f32 v7, vcc, 1.0, v228, 1.0
	v_fma_f32 v24, -v4, v6, 1.0
	v_fmac_f32_e32 v6, v24, v6
	v_mul_f32_e32 v24, v7, v6
	v_fma_f32 v25, -v4, v24, v7
	v_fmac_f32_e32 v24, v25, v6
	v_fma_f32 v4, -v4, v24, v7
	v_div_fmas_f32 v6, v4, v6, v24
	v_div_fixup_f32 v228, v6, v228, 1.0
	v_lshlrev_b32_e32 v4, 16, v28
	v_and_b32_e32 v6, 0xffff0000, v28
	v_lshlrev_b32_e32 v7, 16, v29
	v_and_b32_e32 v24, 0xffff0000, v29
	v_lshlrev_b32_e32 v25, 16, v30
	v_and_b32_e32 v164, 0xffff0000, v30
	v_lshlrev_b32_e32 v165, 16, v31
	v_and_b32_e32 v192, 0xffff0000, v31
	v_fma_f32 v4, v8, v228, -v4
	v_fma_f32 v6, v9, v228, -v6
	v_fma_f32 v7, v10, v228, -v7
	v_fma_f32 v24, v11, v228, -v24
	v_fma_f32 v25, v12, v228, -v25
	v_fma_f32 v164, v13, v228, -v164
	v_fma_f32 v165, v14, v228, -v165
	v_fma_f32 v192, v15, v228, -v192
	v_cvt_pk_bf16_f32 v28, v4, v6
	v_cvt_pk_bf16_f32 v29, v7, v24
	v_cvt_pk_bf16_f32 v30, v25, v164
	v_cvt_pk_bf16_f32 v31, v165, v192
	global_store_dwordx4 v0, v[28:31], s[30:31] offset:2048
	s_add_u32 s30, s30, 0x1000
	s_addc_u32 s31, s31, 0
	v_lshlrev_b32_e32 v4, 16, v32
	v_and_b32_e32 v6, 0xffff0000, v32
	v_lshlrev_b32_e32 v7, 16, v33
	v_and_b32_e32 v24, 0xffff0000, v33
	v_lshlrev_b32_e32 v25, 16, v34
	v_and_b32_e32 v164, 0xffff0000, v34
	v_lshlrev_b32_e32 v165, 16, v35
	v_and_b32_e32 v192, 0xffff0000, v35
	v_add_f32_e32 v8, v8, v4
	v_add_f32_e32 v9, v9, v6
	v_add_f32_e32 v10, v10, v7
	v_add_f32_e32 v11, v11, v24
	v_add_f32_e32 v12, v12, v25
	v_add_f32_e32 v13, v13, v164
	v_add_f32_e32 v14, v14, v165
	v_add_f32_e32 v15, v15, v192
	s_mov_b32 exec_lo, 0xffffffff
	s_mov_b32 exec_hi, 0xffff
	v_lshlrev_b32_e32 v4, 16, v16
	v_and_b32_e32 v6, 0xffff0000, v16
	v_lshlrev_b32_e32 v7, 16, v17
	v_and_b32_e32 v24, 0xffff0000, v17
	v_lshlrev_b32_e32 v25, 16, v18
	v_and_b32_e32 v164, 0xffff0000, v18
	v_lshlrev_b32_e32 v165, 16, v19
	v_and_b32_e32 v192, 0xffff0000, v19
	v_sub_f32_e32 v8, v8, v4
	v_sub_f32_e32 v9, v9, v6
	v_sub_f32_e32 v10, v10, v7
	v_sub_f32_e32 v11, v11, v24
	v_sub_f32_e32 v12, v12, v25
	v_sub_f32_e32 v13, v13, v164
	v_sub_f32_e32 v14, v14, v165
	v_sub_f32_e32 v15, v15, v192
	s_mov_b32 exec_lo, -1
	s_mov_b32 exec_hi, -1
	global_load_dwordx4 v[28:31], v237, s[28:29] offset:3072
	global_load_dwordx4 v[32:35], v36, s[28:29] offset:3072
	global_load_dwordx4 v[16:19], v37, s[28:29] offset:3072
	s_add_u32 s28, s28, 0x1000
	s_addc_u32 s29, s29, 0
	v_ffbl_b32_e32 v6, v26
	v_sub_u32_e32 v6, 0x7e, v6
	v_lshlrev_b32_e32 v228, 23, v6
	s_mov_b32 s25, 0
; __device__ __forceinline__ unsigned cvt_pk_bf16(float lo, float hi) { unsigned r; asm volatile("v_cvt_pk_bf16_f32 %0, %1, %2" : "=v"(r) : "v"(lo), "v"(hi)); return r; }
; __device__ __forceinline__ float bflo(unsigned w) { return __uint_as_float(w << 16); }
; __device__ __forceinline__ float bfhi(unsigned w) { return __uint_as_float(w & 0xffff0000u); }
; #define POOL_ACC(V_, sg) do { s0 += sg bflo(V_.x); s1 += sg bfhi(V_.x); s2 += sg bflo(V_.y); s3 += sg bfhi(V_.y); s4 += sg bflo(V_.z); s5 += sg bfhi(V_.z); s6 += sg bflo(V_.w); s7 += sg bfhi(V_.w); } while (0)
; __device__ __forceinline__ void pool_phase(const bf16_t* zp, bf16_t* mixed, const int wave_s) {
;     ...
;         for (int i = 0; i < 64; ++i) {
;             const int sp = pos0 + i, lo = max(sp - half, 0), hi = min(sp + half - 1, S - 1);
;             const float ic = 1.0f / (float)(hi - lo + 1);
;             const u32x4 w = *(const u32x4*)(zs + (size_t)sp * 512);
;             u32x4 o;
;             o.x = cvt_pk_bf16(s0 * ic - bflo(w.x), s1 * ic - bfhi(w.x)); o.y = cvt_pk_bf16(s2 * ic - bflo(w.y), s3 * ic - bfhi(w.y));
;             o.z = cvt_pk_bf16(s4 * ic - bflo(w.z), s5 * ic - bfhi(w.z)); o.w = cvt_pk_bf16(s6 * ic - bflo(w.w), s7 * ic - bfhi(w.w));
;             *(u32x4*)(ms + (size_t)sp * DM) = o;
;             const int jn = sp + half, jo = sp - half;
;             if (jn < S) { const u32x4 wn = *(const u32x4*)(zs + (size_t)jn * 512); POOL_ACC(wn, +); }
;             if (jo >= 0) { const u32x4 wo = *(const u32x4*)(zs + (size_t)jo * 512); POOL_ACC(wo, -); }
.Lpool_loop_first:
	s_waitcnt vmcnt(9)
	v_lshlrev_b32_e32 v4, 16, v160
	v_and_b32_e32 v6, 0xffff0000, v160
	v_lshlrev_b32_e32 v7, 16, v161
	v_and_b32_e32 v24, 0xffff0000, v161
	v_lshlrev_b32_e32 v25, 16, v162
	v_and_b32_e32 v164, 0xffff0000, v162
	v_lshlrev_b32_e32 v165, 16, v163
	v_and_b32_e32 v192, 0xffff0000, v163
	v_fma_f32 v4, v8, v228, -v4
	v_fma_f32 v6, v9, v228, -v6
	v_fma_f32 v7, v10, v228, -v7
	v_fma_f32 v24, v11, v228, -v24
	v_fma_f32 v25, v12, v228, -v25
	v_fma_f32 v164, v13, v228, -v164
	v_fma_f32 v165, v14, v228, -v165
	v_fma_f32 v192, v15, v228, -v192
	v_cvt_pk_bf16_f32 v160, v4, v6
	v_cvt_pk_bf16_f32 v161, v7, v24
	v_cvt_pk_bf16_f32 v162, v25, v164
	v_cvt_pk_bf16_f32 v163, v165, v192
	global_store_dwordx4 v0, v[160:163], s[30:31]
	v_lshlrev_b32_e32 v4, 16, v168
	v_and_b32_e32 v6, 0xffff0000, v168
	v_lshlrev_b32_e32 v7, 16, v169
	v_and_b32_e32 v24, 0xffff0000, v169
	v_lshlrev_b32_e32 v25, 16, v170
	v_and_b32_e32 v164, 0xffff0000, v170
	v_lshlrev_b32_e32 v165, 16, v171
	v_and_b32_e32 v192, 0xffff0000, v171
	v_add_f32_e32 v8, v8, v4
	v_add_f32_e32 v9, v9, v6
	v_add_f32_e32 v10, v10, v7
	v_add_f32_e32 v11, v11, v24
	v_add_f32_e32 v12, v12, v25
	v_add_f32_e32 v13, v13, v164
	v_add_f32_e32 v14, v14, v165
	v_add_f32_e32 v15, v15, v192
	v_lshlrev_b32_e32 v4, 16, v172
	v_and_b32_e32 v6, 0xffff0000, v172
	v_lshlrev_b32_e32 v7, 16, v173
	v_and_b32_e32 v24, 0xffff0000, v173
	v_lshlrev_b32_e32 v25, 16, v174
	v_and_b32_e32 v164, 0xffff0000, v174
	v_lshlrev_b32_e32 v165, 16, v175
	v_and_b32_e32 v192, 0xffff0000, v175
	v_sub_f32_e32 v8, v8, v4
	v_sub_f32_e32 v9, v9, v6
	v_sub_f32_e32 v10, v10, v7
	v_sub_f32_e32 v11, v11, v24
	v_sub_f32_e32 v12, v12, v25
	v_sub_f32_e32 v13, v13, v164
	v_sub_f32_e32 v14, v14, v165
	v_sub_f32_e32 v15, v15, v192
	global_load_dwordx4 v[160:163], v237, s[28:29]
	global_load_dwordx4 v[168:171], v36, s[28:29]
	global_load_dwordx4 v[172:175], v37, s[28:29]
	s_waitcnt vmcnt(9)
	v_lshlrev_b32_e32 v4, 16, v180
	v_and_b32_e32 v6, 0xffff0000, v180
	v_lshlrev_b32_e32 v7, 16, v181
	v_and_b32_e32 v24, 0xffff0000, v181
	v_lshlrev_b32_e32 v25, 16, v182
	v_and_b32_e32 v164, 0xffff0000, v182
	v_lshlrev_b32_e32 v165, 16, v183
	v_and_b32_e32 v192, 0xffff0000, v183
	v_fma_f32 v4, v8, v228, -v4
	v_fma_f32 v6, v9, v228, -v6
	v_fma_f32 v7, v10, v228, -v7
	v_fma_f32 v24, v11, v228, -v24
	v_fma_f32 v25, v12, v228, -v25
	v_fma_f32 v164, v13, v228, -v164
	v_fma_f32 v165, v14, v228, -v165
	v_fma_f32 v192, v15, v228, -v192
	v_cvt_pk_bf16_f32 v180, v4, v6
	v_cvt_pk_bf16_f32 v181, v7, v24
	v_cvt_pk_bf16_f32 v182, v25, v164
	v_cvt_pk_bf16_f32 v183, v165, v192
	global_store_dwordx4 v0, v[180:183], s[30:31] offset:2048
	s_add_u32 s30, s30, 0x1000
	s_addc_u32 s31, s31, 0
	v_lshlrev_b32_e32 v4, 16, v184
	v_and_b32_e32 v6, 0xffff0000, v184
	v_lshlrev_b32_e32 v7, 16, v185
	v_and_b32_e32 v24, 0xffff0000, v185
	v_lshlrev_b32_e32 v25, 16, v186
	v_and_b32_e32 v164, 0xffff0000, v186
	v_lshlrev_b32_e32 v165, 16, v187
	v_and_b32_e32 v192, 0xffff0000, v187
	v_add_f32_e32 v8, v8, v4
	v_add_f32_e32 v9, v9, v6
	v_add_f32_e32 v10, v10, v7
	v_add_f32_e32 v11, v11, v24
	v_add_f32_e32 v12, v12, v25
	v_add_f32_e32 v13, v13, v164
	v_add_f32_e32 v14, v14, v165
	v_add_f32_e32 v15, v15, v192
	v_lshlrev_b32_e32 v4, 16, v188
	v_and_b32_e32 v6, 0xffff0000, v188
	v_lshlrev_b32_e32 v7, 16, v189
	v_and_b32_e32 v24, 0xffff0000, v189
	v_lshlrev_b32_e32 v25, 16, v190
	v_and_b32_e32 v164, 0xffff0000, v190
	v_lshlrev_b32_e32 v165, 16, v191
	v_and_b32_e32 v192, 0xffff0000, v191
	v_sub_f32_e32 v8, v8, v4
	v_sub_f32_e32 v9, v9, v6
	v_sub_f32_e32 v10, v10, v7
	v_sub_f32_e32 v11, v11, v24
	v_sub_f32_e32 v12, v12, v25
	v_sub_f32_e32 v13, v13, v164
	v_sub_f32_e32 v14, v14, v165
	v_sub_f32_e32 v15, v15, v192
	global_load_dwordx4 v[180:183], v237, s[28:29] offset:1024
	global_load_dwordx4 v[184:187], v36, s[28:29] offset:1024
	global_load_dwordx4 v[188:191], v37, s[28:29] offset:1024
	s_waitcnt vmcnt(9)
	v_lshlrev_b32_e32 v4, 16, v246
	v_and_b32_e32 v6, 0xffff0000, v246
	v_lshlrev_b32_e32 v7, 16, v247
	v_and_b32_e32 v24, 0xffff0000, v247
	v_lshlrev_b32_e32 v25, 16, v248
	v_and_b32_e32 v164, 0xffff0000, v248
	v_lshlrev_b32_e32 v165, 16, v249
	v_and_b32_e32 v192, 0xffff0000, v249
	v_fma_f32 v4, v8, v228, -v4
	v_fma_f32 v6, v9, v228, -v6
	v_fma_f32 v7, v10, v228, -v7
	v_fma_f32 v24, v11, v228, -v24
	v_fma_f32 v25, v12, v228, -v25
	v_fma_f32 v164, v13, v228, -v164
	v_fma_f32 v165, v14, v228, -v165
	v_fma_f32 v192, v15, v228, -v192
	v_cvt_pk_bf16_f32 v246, v4, v6
	v_cvt_pk_bf16_f32 v247, v7, v24
	v_cvt_pk_bf16_f32 v248, v25, v164
	v_cvt_pk_bf16_f32 v249, v165, v192
	global_store_dwordx4 v0, v[246:249], s[30:31]
	v_lshlrev_b32_e32 v4, 16, v250
	v_and_b32_e32 v6, 0xffff0000, v250
	v_lshlrev_b32_e32 v7, 16, v251
	v_and_b32_e32 v24, 0xffff0000, v251
	v_lshlrev_b32_e32 v25, 16, v252
	v_and_b32_e32 v164, 0xffff0000, v252
	v_lshlrev_b32_e32 v165, 16, v253
	v_and_b32_e32 v192, 0xffff0000, v253
	v_add_f32_e32 v8, v8, v4
	v_add_f32_e32 v9, v9, v6
	v_add_f32_e32 v10, v10, v7
	v_add_f32_e32 v11, v11, v24
	v_add_f32_e32 v12, v12, v25
	v_add_f32_e32 v13, v13, v164
	v_add_f32_e32 v14, v14, v165
	v_add_f32_e32 v15, v15, v192
	v_lshlrev_b32_e32 v4, 16, v20
	v_and_b32_e32 v6, 0xffff0000, v20
	v_lshlrev_b32_e32 v7, 16, v21
	v_and_b32_e32 v24, 0xffff0000, v21
	v_lshlrev_b32_e32 v25, 16, v22
	v_and_b32_e32 v164, 0xffff0000, v22
	v_lshlrev_b32_e32 v165, 16, v23
	v_and_b32_e32 v192, 0xffff0000, v23
	v_sub_f32_e32 v8, v8, v4
	v_sub_f32_e32 v9, v9, v6
	v_sub_f32_e32 v10, v10, v7
	v_sub_f32_e32 v11, v11, v24
	v_sub_f32_e32 v12, v12, v25
	v_sub_f32_e32 v13, v13, v164
	v_sub_f32_e32 v14, v14, v165
	v_sub_f32_e32 v15, v15, v192
	global_load_dwordx4 v[246:249], v237, s[28:29] offset:2048
	global_load_dwordx4 v[250:253], v36, s[28:29] offset:2048
	global_load_dwordx4 v[20:23], v37, s[28:29] offset:2048
	s_waitcnt vmcnt(9)
; __device__ __forceinline__ unsigned cvt_pk_bf16(float lo, float hi) { unsigned r; asm volatile("v_cvt_pk_bf16_f32 %0, %1, %2" : "=v"(r) : "v"(lo), "v"(hi)); return r; }
; __device__ __forceinline__ float bflo(unsigned w) { return __uint_as_float(w << 16); }
; __device__ __forceinline__ float bfhi(unsigned w) { return __uint_as_float(w & 0xffff0000u); }
; #define POOL_ACC(V_, sg) do { s0 += sg bflo(V_.x); s1 += sg bfhi(V_.x); s2 += sg bflo(V_.y); s3 += sg bfhi(V_.y); s4 += sg bflo(V_.z); s5 += sg bfhi(V_.z); s6 += sg bflo(V_.w); s7 += sg bfhi(V_.w); } while (0)
; __device__ __forceinline__ void pool_phase(const bf16_t* zp, bf16_t* mixed, const int wave_s) {
;     ...
;         const int tok_base = r * 64, S = tok_base < NPROMPT ? SEQP : SEQS, pos0 = tok_base & (S - 1);
;         const bf16_t* zs = zp + (size_t)(tok_base - pos0) * 512 + c0;
;         bf16_t* ms = mixed + (size_t)(tok_base - pos0) * DM + 512 + c0;
;         float s0 = 0.f, s1 = 0.f, s2 = 0.f, s3 = 0.f, s4 = 0.f, s5 = 0.f, s6 = 0.f, s7 = 0.f;
;     ...
; #pragma unroll
;         for (int d = -8; d < 8; ++d) { const int j = pos0 + d; if (d >= -half && d < half && j >= 0 && j < S) { const u32x4 w = *(const u32x4*)(zs + (size_t)j * 512); POOL_ACC(w, +); } }
;     ...
;         for (int i = 0; i < 64; ++i) {
;             const int sp = pos0 + i, lo = max(sp - half, 0), hi = min(sp + half - 1, S - 1);
;             const float ic = 1.0f / (float)(hi - lo + 1);
;             const u32x4 w = *(const u32x4*)(zs + (size_t)sp * 512);
;             u32x4 o;
;             o.x = cvt_pk_bf16(s0 * ic - bflo(w.x), s1 * ic - bfhi(w.x)); o.y = cvt_pk_bf16(s2 * ic - bflo(w.y), s3 * ic - bfhi(w.y));
;             o.z = cvt_pk_bf16(s4 * ic - bflo(w.z), s5 * ic - bfhi(w.z)); o.w = cvt_pk_bf16(s6 * ic - bflo(w.w), s7 * ic - bfhi(w.w));
;             *(u32x4*)(ms + (size_t)sp * DM) = o;
;             const int jn = sp + half, jo = sp - half;
;             if (jn < S) { const u32x4 wn = *(const u32x4*)(zs + (size_t)jn * 512); POOL_ACC(wn, +); }
;             if (jo >= 0) { const u32x4 wo = *(const u32x4*)(zs + (size_t)jo * 512); POOL_ACC(wo, -); }
	v_lshlrev_b32_e32 v4, 16, v28
	v_and_b32_e32 v6, 0xffff0000, v28
	v_lshlrev_b32_e32 v7, 16, v29
	v_and_b32_e32 v24, 0xffff0000, v29
	v_lshlrev_b32_e32 v25, 16, v30
	v_and_b32_e32 v164, 0xffff0000, v30
	v_lshlrev_b32_e32 v165, 16, v31
	v_and_b32_e32 v192, 0xffff0000, v31
	v_fma_f32 v4, v8, v228, -v4
	v_fma_f32 v6, v9, v228, -v6
	v_fma_f32 v7, v10, v228, -v7
	v_fma_f32 v24, v11, v228, -v24
	v_fma_f32 v25, v12, v228, -v25
	v_fma_f32 v164, v13, v228, -v164
	v_fma_f32 v165, v14, v228, -v165
	v_fma_f32 v192, v15, v228, -v192
	v_cvt_pk_bf16_f32 v28, v4, v6
	v_cvt_pk_bf16_f32 v29, v7, v24
	v_cvt_pk_bf16_f32 v30, v25, v164
	v_cvt_pk_bf16_f32 v31, v165, v192
	global_store_dwordx4 v0, v[28:31], s[30:31] offset:2048
	s_add_u32 s30, s30, 0x1000
	s_addc_u32 s31, s31, 0
	v_lshlrev_b32_e32 v4, 16, v32
	v_and_b32_e32 v6, 0xffff0000, v32
	v_lshlrev_b32_e32 v7, 16, v33
	v_and_b32_e32 v24, 0xffff0000, v33
	v_lshlrev_b32_e32 v25, 16, v34
	v_and_b32_e32 v164, 0xffff0000, v34
	v_lshlrev_b32_e32 v165, 16, v35
	v_and_b32_e32 v192, 0xffff0000, v35
	v_add_f32_e32 v8, v8, v4
	v_add_f32_e32 v9, v9, v6
	v_add_f32_e32 v10, v10, v7
	v_add_f32_e32 v11, v11, v24
	v_add_f32_e32 v12, v12, v25
	v_add_f32_e32 v13, v13, v164
	v_add_f32_e32 v14, v14, v165
	v_add_f32_e32 v15, v15, v192
	v_lshlrev_b32_e32 v4, 16, v16
	v_and_b32_e32 v6, 0xffff0000, v16
	v_lshlrev_b32_e32 v7, 16, v17
	v_and_b32_e32 v24, 0xffff0000, v17
	v_lshlrev_b32_e32 v25, 16, v18
	v_and_b32_e32 v164, 0xffff0000, v18
	v_lshlrev_b32_e32 v165, 16, v19
	v_and_b32_e32 v192, 0xffff0000, v19
	v_sub_f32_e32 v8, v8, v4
	v_sub_f32_e32 v9, v9, v6
	v_sub_f32_e32 v10, v10, v7
	v_sub_f32_e32 v11, v11, v24
	v_sub_f32_e32 v12, v12, v25
	v_sub_f32_e32 v13, v13, v164
	v_sub_f32_e32 v14, v14, v165
	v_sub_f32_e32 v15, v15, v192
	global_load_dwordx4 v[28:31], v237, s[28:29] offset:3072
	global_load_dwordx4 v[32:35], v36, s[28:29] offset:3072
	global_load_dwordx4 v[16:19], v37, s[28:29] offset:3072
	s_add_u32 s28, s28, 0x1000
	s_addc_u32 s29, s29, 0
	s_add_i32 s25, s25, 1
	s_cmp_lt_u32 s25, 14
	s_cbranch_scc1 .Lpool_loop_first
	s_waitcnt vmcnt(0)
	s_branch .LBB0_311
.Lpool_last:
	s_lshl_b32 s25, s3, 10
	s_add_u32 s28, s80, s25
	s_addc_u32 s29, s81, 0
	s_add_u32 s28, s28, 0x199fe000
	s_addc_u32 s29, s29, 0
	s_lshl_b32 s25, s3, 11
	s_add_u32 s30, s80, s25
	s_addc_u32 s31, s81, 0
	s_add_u32 s30, s30, 0x21a00400
	s_addc_u32 s31, s31, 0
	s_mov_b64 s[40:41], s[28:29]
	global_load_dwordx4 v[160:163], v0, s[40:41]
	global_load_dwordx4 v[168:171], v0, s[40:41] offset:1024
	global_load_dwordx4 v[172:175], v0, s[40:41] offset:2048
	global_load_dwordx4 v[180:183], v0, s[40:41] offset:3072
	s_add_u32 s40, s40, 0x1000
	s_addc_u32 s41, s41, 0
	global_load_dwordx4 v[184:187], v0, s[40:41]
	global_load_dwordx4 v[188:191], v0, s[40:41] offset:1024
	global_load_dwordx4 v[246:249], v0, s[40:41] offset:2048
	global_load_dwordx4 v[250:253], v0, s[40:41] offset:3072
	s_add_u32 s40, s40, 0x1000
	s_addc_u32 s41, s41, 0
	v_lshlrev_b32_e32 v4, 10, v26
	v_add_u32_e32 v237, 0x2000, v0
	v_add_u32_e32 v36, v237, v4
	v_sub_u32_e32 v37, v237, v4
	v_ffbl_b32_e32 v6, v26
	v_sub_u32_e32 v6, 0x7e, v6
	v_lshlrev_b32_e32 v228, 23, v6
	v_mov_b32_e32 v8, 0
	v_mov_b32_e32 v9, 0
	v_mov_b32_e32 v10, 0
	v_mov_b32_e32 v11, 0
	v_mov_b32_e32 v12, 0
	v_mov_b32_e32 v13, 0
	v_mov_b32_e32 v14, 0
	v_mov_b32_e32 v15, 0
	s_waitcnt vmcnt(7)
	s_mov_b32 exec_lo, 0
	s_mov_b32 exec_hi, 0xffff0000
	v_lshlrev_b32_e32 v4, 16, v160
	v_and_b32_e32 v6, 0xffff0000, v160
	v_lshlrev_b32_e32 v7, 16, v161
	v_and_b32_e32 v24, 0xffff0000, v161
	v_lshlrev_b32_e32 v25, 16, v162
	v_and_b32_e32 v164, 0xffff0000, v162
	v_lshlrev_b32_e32 v165, 16, v163
	v_and_b32_e32 v192, 0xffff0000, v163
	v_add_f32_e32 v8, v8, v4
	v_add_f32_e32 v9, v9, v6
	v_add_f32_e32 v10, v10, v7
	v_add_f32_e32 v11, v11, v24
	v_add_f32_e32 v12, v12, v25
	v_add_f32_e32 v13, v13, v164
	v_add_f32_e32 v14, v14, v165
	v_add_f32_e32 v15, v15, v192
	s_waitcnt vmcnt(6)
	v_lshlrev_b32_e32 v4, 16, v168
	v_and_b32_e32 v6, 0xffff0000, v168
	v_lshlrev_b32_e32 v7, 16, v169
	v_and_b32_e32 v24, 0xffff0000, v169
	v_lshlrev_b32_e32 v25, 16, v170
	v_and_b32_e32 v164, 0xffff0000, v170
	v_lshlrev_b32_e32 v165, 16, v171
	v_and_b32_e32 v192, 0xffff0000, v171
	v_add_f32_e32 v8, v8, v4
	v_add_f32_e32 v9, v9, v6
	v_add_f32_e32 v10, v10, v7
	v_add_f32_e32 v11, v11, v24
	v_add_f32_e32 v12, v12, v25
	v_add_f32_e32 v13, v13, v164
	v_add_f32_e32 v14, v14, v165
	v_add_f32_e32 v15, v15, v192
	s_waitcnt vmcnt(5)
	v_lshlrev_b32_e32 v4, 16, v172
	v_and_b32_e32 v6, 0xffff0000, v172
	v_lshlrev_b32_e32 v7, 16, v173
	v_and_b32_e32 v24, 0xffff0000, v173
	v_lshlrev_b32_e32 v25, 16, v174
	v_and_b32_e32 v164, 0xffff0000, v174
	v_lshlrev_b32_e32 v165, 16, v175
	v_and_b32_e32 v192, 0xffff0000, v175
	v_add_f32_e32 v8, v8, v4
	v_add_f32_e32 v9, v9, v6
	v_add_f32_e32 v10, v10, v7
	v_add_f32_e32 v11, v11, v24
	v_add_f32_e32 v12, v12, v25
	v_add_f32_e32 v13, v13, v164
	v_add_f32_e32 v14, v14, v165
	v_add_f32_e32 v15, v15, v192
	s_waitcnt vmcnt(4)
	v_lshlrev_b32_e32 v4, 16, v180
	v_and_b32_e32 v6, 0xffff0000, v180
	v_lshlrev_b32_e32 v7, 16, v181
	v_and_b32_e32 v24, 0xffff0000, v181
	v_lshlrev_b32_e32 v25, 16, v182
	v_and_b32_e32 v164, 0xffff0000, v182
	v_lshlrev_b32_e32 v165, 16, v183
	v_and_b32_e32 v192, 0xffff0000, v183
	v_add_f32_e32 v8, v8, v4
	v_add_f32_e32 v9, v9, v6
	v_add_f32_e32 v10, v10, v7
	v_add_f32_e32 v11, v11, v24
	v_add_f32_e32 v12, v12, v25
	v_add_f32_e32 v13, v13, v164
	v_add_f32_e32 v14, v14, v165
	v_add_f32_e32 v15, v15, v192
	s_waitcnt vmcnt(3)
; #define POOL_ACC(V_, sg) do { s0 += sg bflo(V_.x); s1 += sg bfhi(V_.x); s2 += sg bflo(V_.y); s3 += sg bfhi(V_.y); s4 += sg bflo(V_.z); s5 += sg bfhi(V_.z); s6 += sg bflo(V_.w); s7 += sg bfhi(V_.w); } while (0)
; __device__ __forceinline__ void pool_phase(const bf16_t* zp, bf16_t* mixed, const int wave_s) {
;     ...
;         const int tok_base = r * 64, S = tok_base < NPROMPT ? SEQP : SEQS, pos0 = tok_base & (S - 1);
;         const bf16_t* zs = zp + (size_t)(tok_base - pos0) * 512 + c0;
;         bf16_t* ms = mixed + (size_t)(tok_base - pos0) * DM + 512 + c0;
;         float s0 = 0.f, s1 = 0.f, s2 = 0.f, s3 = 0.f, s4 = 0.f, s5 = 0.f, s6 = 0.f, s7 = 0.f;
;     ...
; #pragma unroll
;         for (int d = -8; d < 8; ++d) { const int j = pos0 + d; if (d >= -half && d < half && j >= 0 && j < S) { const u32x4 w = *(const u32x4*)(zs + (size_t)j * 512); POOL_ACC(w, +); } }
	s_mov_b32 exec_lo, 0
	s_mov_b32 exec_hi, 0xffffffff
	v_lshlrev_b32_e32 v4, 16, v184
	v_and_b32_e32 v6, 0xffff0000, v184
	v_lshlrev_b32_e32 v7, 16, v185
	v_and_b32_e32 v24, 0xffff0000, v185
	v_lshlrev_b32_e32 v25, 16, v186
	v_and_b32_e32 v164, 0xffff0000, v186
	v_lshlrev_b32_e32 v165, 16, v187
	v_and_b32_e32 v192, 0xffff0000, v187
	v_add_f32_e32 v8, v8, v4
	v_add_f32_e32 v9, v9, v6
	v_add_f32_e32 v10, v10, v7
	v_add_f32_e32 v11, v11, v24
	v_add_f32_e32 v12, v12, v25
	v_add_f32_e32 v13, v13, v164
	v_add_f32_e32 v14, v14, v165
	v_add_f32_e32 v15, v15, v192
	s_waitcnt vmcnt(2)
	v_lshlrev_b32_e32 v4, 16, v188
	v_and_b32_e32 v6, 0xffff0000, v188
	v_lshlrev_b32_e32 v7, 16, v189
	v_and_b32_e32 v24, 0xffff0000, v189
	v_lshlrev_b32_e32 v25, 16, v190
	v_and_b32_e32 v164, 0xffff0000, v190
	v_lshlrev_b32_e32 v165, 16, v191
	v_and_b32_e32 v192, 0xffff0000, v191
	v_add_f32_e32 v8, v8, v4
	v_add_f32_e32 v9, v9, v6
	v_add_f32_e32 v10, v10, v7
	v_add_f32_e32 v11, v11, v24
	v_add_f32_e32 v12, v12, v25
	v_add_f32_e32 v13, v13, v164
	v_add_f32_e32 v14, v14, v165
	v_add_f32_e32 v15, v15, v192
	s_waitcnt vmcnt(1)
	s_mov_b32 exec_lo, 0xffff0000
	s_mov_b32 exec_hi, 0xffffffff
	v_lshlrev_b32_e32 v4, 16, v246
	v_and_b32_e32 v6, 0xffff0000, v246
	v_lshlrev_b32_e32 v7, 16, v247
	v_and_b32_e32 v24, 0xffff0000, v247
	v_lshlrev_b32_e32 v25, 16, v248
	v_and_b32_e32 v164, 0xffff0000, v248
	v_lshlrev_b32_e32 v165, 16, v249
	v_and_b32_e32 v192, 0xffff0000, v249
	v_add_f32_e32 v8, v8, v4
	v_add_f32_e32 v9, v9, v6
	v_add_f32_e32 v10, v10, v7
	v_add_f32_e32 v11, v11, v24
	v_add_f32_e32 v12, v12, v25
	v_add_f32_e32 v13, v13, v164
	v_add_f32_e32 v14, v14, v165
	v_add_f32_e32 v15, v15, v192
	s_waitcnt vmcnt(0)
	s_mov_b32 exec_lo, 0xffffffff
	s_mov_b32 exec_hi, 0xffffffff
	v_lshlrev_b32_e32 v4, 16, v250
	v_and_b32_e32 v6, 0xffff0000, v250
	v_lshlrev_b32_e32 v7, 16, v251
	v_and_b32_e32 v24, 0xffff0000, v251
	v_lshlrev_b32_e32 v25, 16, v252
	v_and_b32_e32 v164, 0xffff0000, v252
	v_lshlrev_b32_e32 v165, 16, v253
	v_and_b32_e32 v192, 0xffff0000, v253
	v_add_f32_e32 v8, v8, v4
	v_add_f32_e32 v9, v9, v6
	v_add_f32_e32 v10, v10, v7
	v_add_f32_e32 v11, v11, v24
	v_add_f32_e32 v12, v12, v25
	v_add_f32_e32 v13, v13, v164
	v_add_f32_e32 v14, v14, v165
	v_add_f32_e32 v15, v15, v192
	global_load_dwordx4 v[160:163], v0, s[40:41]
	global_load_dwordx4 v[168:171], v0, s[40:41] offset:1024
	global_load_dwordx4 v[172:175], v0, s[40:41] offset:2048
	global_load_dwordx4 v[180:183], v0, s[40:41] offset:3072
	s_add_u32 s40, s40, 0x1000
	s_addc_u32 s41, s41, 0
	global_load_dwordx4 v[184:187], v0, s[40:41]
	global_load_dwordx4 v[188:191], v0, s[40:41] offset:1024
	global_load_dwordx4 v[246:249], v0, s[40:41] offset:2048
	global_load_dwordx4 v[250:253], v0, s[40:41] offset:3072
	s_add_u32 s40, s40, 0x1000
	s_addc_u32 s41, s41, 0
	s_waitcnt vmcnt(7)
	v_lshlrev_b32_e32 v4, 16, v160
	v_and_b32_e32 v6, 0xffff0000, v160
	v_lshlrev_b32_e32 v7, 16, v161
	v_and_b32_e32 v24, 0xffff0000, v161
	v_lshlrev_b32_e32 v25, 16, v162
	v_and_b32_e32 v164, 0xffff0000, v162
	v_lshlrev_b32_e32 v165, 16, v163
	v_and_b32_e32 v192, 0xffff0000, v163
	v_add_f32_e32 v8, v8, v4
	v_add_f32_e32 v9, v9, v6
	v_add_f32_e32 v10, v10, v7
	v_add_f32_e32 v11, v11, v24
	v_add_f32_e32 v12, v12, v25
	v_add_f32_e32 v13, v13, v164
	v_add_f32_e32 v14, v14, v165
	v_add_f32_e32 v15, v15, v192
	s_waitcnt vmcnt(6)
	s_mov_b32 exec_lo, 0xffff0000
	s_mov_b32 exec_hi, 0xffffffff
	v_lshlrev_b32_e32 v4, 16, v168
	v_and_b32_e32 v6, 0xffff0000, v168
	v_lshlrev_b32_e32 v7, 16, v169
	v_and_b32_e32 v24, 0xffff0000, v169
	v_lshlrev_b32_e32 v25, 16, v170
	v_and_b32_e32 v164, 0xffff0000, v170
	v_lshlrev_b32_e32 v165, 16, v171
	v_and_b32_e32 v192, 0xffff0000, v171
	v_add_f32_e32 v8, v8, v4
	v_add_f32_e32 v9, v9, v6
	v_add_f32_e32 v10, v10, v7
	v_add_f32_e32 v11, v11, v24
	v_add_f32_e32 v12, v12, v25
	v_add_f32_e32 v13, v13, v164
	v_add_f32_e32 v14, v14, v165
	v_add_f32_e32 v15, v15, v192
	s_waitcnt vmcnt(5)
	s_mov_b32 exec_lo, 0
	s_mov_b32 exec_hi, 0xffffffff
	v_lshlrev_b32_e32 v4, 16, v172
	v_and_b32_e32 v6, 0xffff0000, v172
	v_lshlrev_b32_e32 v7, 16, v173
	v_and_b32_e32 v24, 0xffff0000, v173
	v_lshlrev_b32_e32 v25, 16, v174
	v_and_b32_e32 v164, 0xffff0000, v174
	v_lshlrev_b32_e32 v165, 16, v175
	v_and_b32_e32 v192, 0xffff0000, v175
	v_add_f32_e32 v8, v8, v4
	v_add_f32_e32 v9, v9, v6
	v_add_f32_e32 v10, v10, v7
	v_add_f32_e32 v11, v11, v24
	v_add_f32_e32 v12, v12, v25
	v_add_f32_e32 v13, v13, v164
	v_add_f32_e32 v14, v14, v165
	v_add_f32_e32 v15, v15, v192
	s_waitcnt vmcnt(4)
	v_lshlrev_b32_e32 v4, 16, v180
	v_and_b32_e32 v6, 0xffff0000, v180
	v_lshlrev_b32_e32 v7, 16, v181
	v_and_b32_e32 v24, 0xffff0000, v181
	v_lshlrev_b32_e32 v25, 16, v182
	v_and_b32_e32 v164, 0xffff0000, v182
	v_lshlrev_b32_e32 v165, 16, v183
	v_and_b32_e32 v192, 0xffff0000, v183
	v_add_f32_e32 v8, v8, v4
	v_add_f32_e32 v9, v9, v6
	v_add_f32_e32 v10, v10, v7
	v_add_f32_e32 v11, v11, v24
	v_add_f32_e32 v12, v12, v25
	v_add_f32_e32 v13, v13, v164
	v_add_f32_e32 v14, v14, v165
	v_add_f32_e32 v15, v15, v192
	s_waitcnt vmcnt(3)
	s_mov_b32 exec_lo, 0
	s_mov_b32 exec_hi, 0xffff0000
	v_lshlrev_b32_e32 v4, 16, v184
	v_and_b32_e32 v6, 0xffff0000, v184
	v_lshlrev_b32_e32 v7, 16, v185
	v_and_b32_e32 v24, 0xffff0000, v185
	v_lshlrev_b32_e32 v25, 16, v186
	v_and_b32_e32 v164, 0xffff0000, v186
	v_lshlrev_b32_e32 v165, 16, v187
	v_and_b32_e32 v192, 0xffff0000, v187
	v_add_f32_e32 v8, v8, v4
	v_add_f32_e32 v9, v9, v6
	v_add_f32_e32 v10, v10, v7
	v_add_f32_e32 v11, v11, v24
	v_add_f32_e32 v12, v12, v25
	v_add_f32_e32 v13, v13, v164
	v_add_f32_e32 v14, v14, v165
	v_add_f32_e32 v15, v15, v192
	s_waitcnt vmcnt(2)
; __device__ __forceinline__ unsigned cvt_pk_bf16(float lo, float hi) { unsigned r; asm volatile("v_cvt_pk_bf16_f32 %0, %1, %2" : "=v"(r) : "v"(lo), "v"(hi)); return r; }
; __device__ __forceinline__ float bflo(unsigned w) { return __uint_as_float(w << 16); }
; __device__ __forceinline__ float bfhi(unsigned w) { return __uint_as_float(w & 0xffff0000u); }
; #define POOL_ACC(V_, sg) do { s0 += sg bflo(V_.x); s1 += sg bfhi(V_.x); s2 += sg bflo(V_.y); s3 += sg bfhi(V_.y); s4 += sg bflo(V_.z); s5 += sg bfhi(V_.z); s6 += sg bflo(V_.w); s7 += sg bfhi(V_.w); } while (0)
; __device__ __forceinline__ void pool_phase(const bf16_t* zp, bf16_t* mixed, const int wave_s) {
;     ...
;         for (int d = -8; d < 8; ++d) { const int j = pos0 + d; if (d >= -half && d < half && j >= 0 && j < S) { const u32x4 w = *(const u32x4*)(zs + (size_t)j * 512); POOL_ACC(w, +); } }
; #pragma unroll 4
;         for (int i = 0; i < 64; ++i) {
;             const int sp = pos0 + i, lo = max(sp - half, 0), hi = min(sp + half - 1, S - 1);
;             const float ic = 1.0f / (float)(hi - lo + 1);
;             const u32x4 w = *(const u32x4*)(zs + (size_t)sp * 512);
;             u32x4 o;
;             o.x = cvt_pk_bf16(s0 * ic - bflo(w.x), s1 * ic - bfhi(w.x)); o.y = cvt_pk_bf16(s2 * ic - bflo(w.y), s3 * ic - bfhi(w.y));
;             o.z = cvt_pk_bf16(s4 * ic - bflo(w.z), s5 * ic - bfhi(w.z)); o.w = cvt_pk_bf16(s6 * ic - bflo(w.w), s7 * ic - bfhi(w.w));
;             *(u32x4*)(ms + (size_t)sp * DM) = o;
;             const int jn = sp + half, jo = sp - half;
;             if (jn < S) { const u32x4 wn = *(const u32x4*)(zs + (size_t)jn * 512); POOL_ACC(wn, +); }
;             if (jo >= 0) { const u32x4 wo = *(const u32x4*)(zs + (size_t)jo * 512); POOL_ACC(wo, -); }
	v_lshlrev_b32_e32 v4, 16, v188
	v_and_b32_e32 v6, 0xffff0000, v188
	v_lshlrev_b32_e32 v7, 16, v189
	v_and_b32_e32 v24, 0xffff0000, v189
	v_lshlrev_b32_e32 v25, 16, v190
	v_and_b32_e32 v164, 0xffff0000, v190
	v_lshlrev_b32_e32 v165, 16, v191
	v_and_b32_e32 v192, 0xffff0000, v191
	v_add_f32_e32 v8, v8, v4
	v_add_f32_e32 v9, v9, v6
	v_add_f32_e32 v10, v10, v7
	v_add_f32_e32 v11, v11, v24
	v_add_f32_e32 v12, v12, v25
	v_add_f32_e32 v13, v13, v164
	v_add_f32_e32 v14, v14, v165
	v_add_f32_e32 v15, v15, v192
	s_waitcnt vmcnt(1)
	v_lshlrev_b32_e32 v4, 16, v246
	v_and_b32_e32 v6, 0xffff0000, v246
	v_lshlrev_b32_e32 v7, 16, v247
	v_and_b32_e32 v24, 0xffff0000, v247
	v_lshlrev_b32_e32 v25, 16, v248
	v_and_b32_e32 v164, 0xffff0000, v248
	v_lshlrev_b32_e32 v165, 16, v249
	v_and_b32_e32 v192, 0xffff0000, v249
	v_add_f32_e32 v8, v8, v4
	v_add_f32_e32 v9, v9, v6
	v_add_f32_e32 v10, v10, v7
	v_add_f32_e32 v11, v11, v24
	v_add_f32_e32 v12, v12, v25
	v_add_f32_e32 v13, v13, v164
	v_add_f32_e32 v14, v14, v165
	v_add_f32_e32 v15, v15, v192
	s_waitcnt vmcnt(0)
	v_lshlrev_b32_e32 v4, 16, v250
	v_and_b32_e32 v6, 0xffff0000, v250
	v_lshlrev_b32_e32 v7, 16, v251
	v_and_b32_e32 v24, 0xffff0000, v251
	v_lshlrev_b32_e32 v25, 16, v252
	v_and_b32_e32 v164, 0xffff0000, v252
	v_lshlrev_b32_e32 v165, 16, v253
	v_and_b32_e32 v192, 0xffff0000, v253
	v_add_f32_e32 v8, v8, v4
	v_add_f32_e32 v9, v9, v6
	v_add_f32_e32 v10, v10, v7
	v_add_f32_e32 v11, v11, v24
	v_add_f32_e32 v12, v12, v25
	v_add_f32_e32 v13, v13, v164
	v_add_f32_e32 v14, v14, v165
	v_add_f32_e32 v15, v15, v192
	s_mov_b32 exec_lo, 0xffffffff
	s_mov_b32 exec_hi, 0xffffffff
	global_load_dwordx4 v[160:163], v237, s[28:29]
	global_load_dwordx4 v[168:171], v36, s[28:29]
	global_load_dwordx4 v[172:175], v37, s[28:29]
	global_load_dwordx4 v[180:183], v237, s[28:29] offset:1024
	global_load_dwordx4 v[184:187], v36, s[28:29] offset:1024
	global_load_dwordx4 v[188:191], v37, s[28:29] offset:1024
	global_load_dwordx4 v[246:249], v237, s[28:29] offset:2048
	global_load_dwordx4 v[250:253], v36, s[28:29] offset:2048
	global_load_dwordx4 v[20:23], v37, s[28:29] offset:2048
	global_load_dwordx4 v[28:31], v237, s[28:29] offset:3072
	global_load_dwordx4 v[32:35], v36, s[28:29] offset:3072
	global_load_dwordx4 v[16:19], v37, s[28:29] offset:3072
	s_add_u32 s28, s28, 0x1000
	s_addc_u32 s29, s29, 0
	s_mov_b32 s25, 0
.Lpool_loop_last:
	s_waitcnt vmcnt(9)
	v_lshlrev_b32_e32 v4, 16, v160
	v_and_b32_e32 v6, 0xffff0000, v160
	v_lshlrev_b32_e32 v7, 16, v161
	v_and_b32_e32 v24, 0xffff0000, v161
	v_lshlrev_b32_e32 v25, 16, v162
	v_and_b32_e32 v164, 0xffff0000, v162
	v_lshlrev_b32_e32 v165, 16, v163
	v_and_b32_e32 v192, 0xffff0000, v163
	v_fma_f32 v4, v8, v228, -v4
	v_fma_f32 v6, v9, v228, -v6
	v_fma_f32 v7, v10, v228, -v7
	v_fma_f32 v24, v11, v228, -v24
	v_fma_f32 v25, v12, v228, -v25
	v_fma_f32 v164, v13, v228, -v164
	v_fma_f32 v165, v14, v228, -v165
	v_fma_f32 v192, v15, v228, -v192
	v_cvt_pk_bf16_f32 v160, v4, v6
	v_cvt_pk_bf16_f32 v161, v7, v24
	v_cvt_pk_bf16_f32 v162, v25, v164
	v_cvt_pk_bf16_f32 v163, v165, v192
	global_store_dwordx4 v0, v[160:163], s[30:31]
	v_lshlrev_b32_e32 v4, 16, v168
	v_and_b32_e32 v6, 0xffff0000, v168
	v_lshlrev_b32_e32 v7, 16, v169
	v_and_b32_e32 v24, 0xffff0000, v169
	v_lshlrev_b32_e32 v25, 16, v170
	v_and_b32_e32 v164, 0xffff0000, v170
	v_lshlrev_b32_e32 v165, 16, v171
	v_and_b32_e32 v192, 0xffff0000, v171
	v_add_f32_e32 v8, v8, v4
	v_add_f32_e32 v9, v9, v6
	v_add_f32_e32 v10, v10, v7
	v_add_f32_e32 v11, v11, v24
	v_add_f32_e32 v12, v12, v25
	v_add_f32_e32 v13, v13, v164
	v_add_f32_e32 v14, v14, v165
	v_add_f32_e32 v15, v15, v192
	v_lshlrev_b32_e32 v4, 16, v172
	v_and_b32_e32 v6, 0xffff0000, v172
	v_lshlrev_b32_e32 v7, 16, v173
	v_and_b32_e32 v24, 0xffff0000, v173
	v_lshlrev_b32_e32 v25, 16, v174
	v_and_b32_e32 v164, 0xffff0000, v174
	v_lshlrev_b32_e32 v165, 16, v175
	v_and_b32_e32 v192, 0xffff0000, v175
	v_sub_f32_e32 v8, v8, v4
	v_sub_f32_e32 v9, v9, v6
	v_sub_f32_e32 v10, v10, v7
	v_sub_f32_e32 v11, v11, v24
	v_sub_f32_e32 v12, v12, v25
	v_sub_f32_e32 v13, v13, v164
	v_sub_f32_e32 v14, v14, v165
	v_sub_f32_e32 v15, v15, v192
	global_load_dwordx4 v[160:163], v237, s[28:29]
	global_load_dwordx4 v[168:171], v36, s[28:29]
	global_load_dwordx4 v[172:175], v37, s[28:29]
	s_waitcnt vmcnt(9)
	v_lshlrev_b32_e32 v4, 16, v180
	v_and_b32_e32 v6, 0xffff0000, v180
	v_lshlrev_b32_e32 v7, 16, v181
	v_and_b32_e32 v24, 0xffff0000, v181
	v_lshlrev_b32_e32 v25, 16, v182
	v_and_b32_e32 v164, 0xffff0000, v182
	v_lshlrev_b32_e32 v165, 16, v183
	v_and_b32_e32 v192, 0xffff0000, v183
	v_fma_f32 v4, v8, v228, -v4
	v_fma_f32 v6, v9, v228, -v6
	v_fma_f32 v7, v10, v228, -v7
	v_fma_f32 v24, v11, v228, -v24
	v_fma_f32 v25, v12, v228, -v25
	v_fma_f32 v164, v13, v228, -v164
	v_fma_f32 v165, v14, v228, -v165
	v_fma_f32 v192, v15, v228, -v192
	v_cvt_pk_bf16_f32 v180, v4, v6
	v_cvt_pk_bf16_f32 v181, v7, v24
	v_cvt_pk_bf16_f32 v182, v25, v164
	v_cvt_pk_bf16_f32 v183, v165, v192
	global_store_dwordx4 v0, v[180:183], s[30:31] offset:2048
	s_add_u32 s30, s30, 0x1000
	s_addc_u32 s31, s31, 0
	v_lshlrev_b32_e32 v4, 16, v184
	v_and_b32_e32 v6, 0xffff0000, v184
	v_lshlrev_b32_e32 v7, 16, v185
	v_and_b32_e32 v24, 0xffff0000, v185
	v_lshlrev_b32_e32 v25, 16, v186
	v_and_b32_e32 v164, 0xffff0000, v186
	v_lshlrev_b32_e32 v165, 16, v187
	v_and_b32_e32 v192, 0xffff0000, v187
	v_add_f32_e32 v8, v8, v4
	v_add_f32_e32 v9, v9, v6
	v_add_f32_e32 v10, v10, v7
	v_add_f32_e32 v11, v11, v24
	v_add_f32_e32 v12, v12, v25
	v_add_f32_e32 v13, v13, v164
	v_add_f32_e32 v14, v14, v165
	v_add_f32_e32 v15, v15, v192
	v_lshlrev_b32_e32 v4, 16, v188
	v_and_b32_e32 v6, 0xffff0000, v188
	v_lshlrev_b32_e32 v7, 16, v189
	v_and_b32_e32 v24, 0xffff0000, v189
	v_lshlrev_b32_e32 v25, 16, v190
	v_and_b32_e32 v164, 0xffff0000, v190
	v_lshlrev_b32_e32 v165, 16, v191
	v_and_b32_e32 v192, 0xffff0000, v191
	v_sub_f32_e32 v8, v8, v4
	v_sub_f32_e32 v9, v9, v6
	v_sub_f32_e32 v10, v10, v7
	v_sub_f32_e32 v11, v11, v24
	v_sub_f32_e32 v12, v12, v25
	v_sub_f32_e32 v13, v13, v164
	v_sub_f32_e32 v14, v14, v165
	v_sub_f32_e32 v15, v15, v192
	global_load_dwordx4 v[180:183], v237, s[28:29] offset:1024
	global_load_dwordx4 v[184:187], v36, s[28:29] offset:1024
	global_load_dwordx4 v[188:191], v37, s[28:29] offset:1024
	s_waitcnt vmcnt(9)
; __device__ __forceinline__ unsigned cvt_pk_bf16(float lo, float hi) { unsigned r; asm volatile("v_cvt_pk_bf16_f32 %0, %1, %2" : "=v"(r) : "v"(lo), "v"(hi)); return r; }
; __device__ __forceinline__ float bflo(unsigned w) { return __uint_as_float(w << 16); }
; __device__ __forceinline__ float bfhi(unsigned w) { return __uint_as_float(w & 0xffff0000u); }
; #define POOL_ACC(V_, sg) do { s0 += sg bflo(V_.x); s1 += sg bfhi(V_.x); s2 += sg bflo(V_.y); s3 += sg bfhi(V_.y); s4 += sg bflo(V_.z); s5 += sg bfhi(V_.z); s6 += sg bflo(V_.w); s7 += sg bfhi(V_.w); } while (0)
; __device__ __forceinline__ void pool_phase(const bf16_t* zp, bf16_t* mixed, const int wave_s) {
;     ...
;         for (int i = 0; i < 64; ++i) {
;             const int sp = pos0 + i, lo = max(sp - half, 0), hi = min(sp + half - 1, S - 1);
;             const float ic = 1.0f / (float)(hi - lo + 1);
;             const u32x4 w = *(const u32x4*)(zs + (size_t)sp * 512);
;             u32x4 o;
;             o.x = cvt_pk_bf16(s0 * ic - bflo(w.x), s1 * ic - bfhi(w.x)); o.y = cvt_pk_bf16(s2 * ic - bflo(w.y), s3 * ic - bfhi(w.y));
;             o.z = cvt_pk_bf16(s4 * ic - bflo(w.z), s5 * ic - bfhi(w.z)); o.w = cvt_pk_bf16(s6 * ic - bflo(w.w), s7 * ic - bfhi(w.w));
;             *(u32x4*)(ms + (size_t)sp * DM) = o;
;             const int jn = sp + half, jo = sp - half;
;             if (jn < S) { const u32x4 wn = *(const u32x4*)(zs + (size_t)jn * 512); POOL_ACC(wn, +); }
;             if (jo >= 0) { const u32x4 wo = *(const u32x4*)(zs + (size_t)jo * 512); POOL_ACC(wo, -); }
	v_lshlrev_b32_e32 v4, 16, v246
	v_and_b32_e32 v6, 0xffff0000, v246
	v_lshlrev_b32_e32 v7, 16, v247
	v_and_b32_e32 v24, 0xffff0000, v247
	v_lshlrev_b32_e32 v25, 16, v248
	v_and_b32_e32 v164, 0xffff0000, v248
	v_lshlrev_b32_e32 v165, 16, v249
	v_and_b32_e32 v192, 0xffff0000, v249
	v_fma_f32 v4, v8, v228, -v4
	v_fma_f32 v6, v9, v228, -v6
	v_fma_f32 v7, v10, v228, -v7
	v_fma_f32 v24, v11, v228, -v24
	v_fma_f32 v25, v12, v228, -v25
	v_fma_f32 v164, v13, v228, -v164
	v_fma_f32 v165, v14, v228, -v165
	v_fma_f32 v192, v15, v228, -v192
	v_cvt_pk_bf16_f32 v246, v4, v6
	v_cvt_pk_bf16_f32 v247, v7, v24
	v_cvt_pk_bf16_f32 v248, v25, v164
	v_cvt_pk_bf16_f32 v249, v165, v192
	global_store_dwordx4 v0, v[246:249], s[30:31]
	v_lshlrev_b32_e32 v4, 16, v250
	v_and_b32_e32 v6, 0xffff0000, v250
	v_lshlrev_b32_e32 v7, 16, v251
	v_and_b32_e32 v24, 0xffff0000, v251
	v_lshlrev_b32_e32 v25, 16, v252
	v_and_b32_e32 v164, 0xffff0000, v252
	v_lshlrev_b32_e32 v165, 16, v253
	v_and_b32_e32 v192, 0xffff0000, v253
	v_add_f32_e32 v8, v8, v4
	v_add_f32_e32 v9, v9, v6
	v_add_f32_e32 v10, v10, v7
	v_add_f32_e32 v11, v11, v24
	v_add_f32_e32 v12, v12, v25
	v_add_f32_e32 v13, v13, v164
	v_add_f32_e32 v14, v14, v165
	v_add_f32_e32 v15, v15, v192
	v_lshlrev_b32_e32 v4, 16, v20
	v_and_b32_e32 v6, 0xffff0000, v20
	v_lshlrev_b32_e32 v7, 16, v21
	v_and_b32_e32 v24, 0xffff0000, v21
	v_lshlrev_b32_e32 v25, 16, v22
	v_and_b32_e32 v164, 0xffff0000, v22
	v_lshlrev_b32_e32 v165, 16, v23
	v_and_b32_e32 v192, 0xffff0000, v23
	v_sub_f32_e32 v8, v8, v4
	v_sub_f32_e32 v9, v9, v6
	v_sub_f32_e32 v10, v10, v7
	v_sub_f32_e32 v11, v11, v24
	v_sub_f32_e32 v12, v12, v25
	v_sub_f32_e32 v13, v13, v164
	v_sub_f32_e32 v14, v14, v165
	v_sub_f32_e32 v15, v15, v192
	global_load_dwordx4 v[246:249], v237, s[28:29] offset:2048
	global_load_dwordx4 v[250:253], v36, s[28:29] offset:2048
	global_load_dwordx4 v[20:23], v37, s[28:29] offset:2048
	s_waitcnt vmcnt(9)
	v_lshlrev_b32_e32 v4, 16, v28
	v_and_b32_e32 v6, 0xffff0000, v28
	v_lshlrev_b32_e32 v7, 16, v29
	v_and_b32_e32 v24, 0xffff0000, v29
	v_lshlrev_b32_e32 v25, 16, v30
	v_and_b32_e32 v164, 0xffff0000, v30
	v_lshlrev_b32_e32 v165, 16, v31
	v_and_b32_e32 v192, 0xffff0000, v31
	v_fma_f32 v4, v8, v228, -v4
	v_fma_f32 v6, v9, v228, -v6
	v_fma_f32 v7, v10, v228, -v7
	v_fma_f32 v24, v11, v228, -v24
	v_fma_f32 v25, v12, v228, -v25
	v_fma_f32 v164, v13, v228, -v164
	v_fma_f32 v165, v14, v228, -v165
	v_fma_f32 v192, v15, v228, -v192
	v_cvt_pk_bf16_f32 v28, v4, v6
	v_cvt_pk_bf16_f32 v29, v7, v24
	v_cvt_pk_bf16_f32 v30, v25, v164
	v_cvt_pk_bf16_f32 v31, v165, v192
	global_store_dwordx4 v0, v[28:31], s[30:31] offset:2048
	s_add_u32 s30, s30, 0x1000
	s_addc_u32 s31, s31, 0
	v_lshlrev_b32_e32 v4, 16, v32
	v_and_b32_e32 v6, 0xffff0000, v32
	v_lshlrev_b32_e32 v7, 16, v33
	v_and_b32_e32 v24, 0xffff0000, v33
	v_lshlrev_b32_e32 v25, 16, v34
	v_and_b32_e32 v164, 0xffff0000, v34
	v_lshlrev_b32_e32 v165, 16, v35
	v_and_b32_e32 v192, 0xffff0000, v35
	v_add_f32_e32 v8, v8, v4
	v_add_f32_e32 v9, v9, v6
	v_add_f32_e32 v10, v10, v7
	v_add_f32_e32 v11, v11, v24
	v_add_f32_e32 v12, v12, v25
	v_add_f32_e32 v13, v13, v164
	v_add_f32_e32 v14, v14, v165
	v_add_f32_e32 v15, v15, v192
	v_lshlrev_b32_e32 v4, 16, v16
	v_and_b32_e32 v6, 0xffff0000, v16
	v_lshlrev_b32_e32 v7, 16, v17
	v_and_b32_e32 v24, 0xffff0000, v17
	v_lshlrev_b32_e32 v25, 16, v18
	v_and_b32_e32 v164, 0xffff0000, v18
	v_lshlrev_b32_e32 v165, 16, v19
	v_and_b32_e32 v192, 0xffff0000, v19
	v_sub_f32_e32 v8, v8, v4
	v_sub_f32_e32 v9, v9, v6
	v_sub_f32_e32 v10, v10, v7
	v_sub_f32_e32 v11, v11, v24
	v_sub_f32_e32 v12, v12, v25
	v_sub_f32_e32 v13, v13, v164
	v_sub_f32_e32 v14, v14, v165
	v_sub_f32_e32 v15, v15, v192
	global_load_dwordx4 v[28:31], v237, s[28:29] offset:3072
	global_load_dwordx4 v[32:35], v36, s[28:29] offset:3072
	global_load_dwordx4 v[16:19], v37, s[28:29] offset:3072
	s_add_u32 s28, s28, 0x1000
	s_addc_u32 s29, s29, 0
	s_add_i32 s25, s25, 1
	s_cmp_lt_u32 s25, 14
	s_cbranch_scc1 .Lpool_loop_last
	s_waitcnt vmcnt(9)
	v_lshlrev_b32_e32 v4, 16, v160
	v_and_b32_e32 v6, 0xffff0000, v160
	v_lshlrev_b32_e32 v7, 16, v161
	v_and_b32_e32 v24, 0xffff0000, v161
	v_lshlrev_b32_e32 v25, 16, v162
	v_and_b32_e32 v164, 0xffff0000, v162
	v_lshlrev_b32_e32 v165, 16, v163
	v_and_b32_e32 v192, 0xffff0000, v163
	v_fma_f32 v4, v8, v228, -v4
	v_fma_f32 v6, v9, v228, -v6
	v_fma_f32 v7, v10, v228, -v7
	v_fma_f32 v24, v11, v228, -v24
	v_fma_f32 v25, v12, v228, -v25
	v_fma_f32 v164, v13, v228, -v164
	v_fma_f32 v165, v14, v228, -v165
	v_fma_f32 v192, v15, v228, -v192
	v_cvt_pk_bf16_f32 v160, v4, v6
	v_cvt_pk_bf16_f32 v161, v7, v24
	v_cvt_pk_bf16_f32 v162, v25, v164
	v_cvt_pk_bf16_f32 v163, v165, v192
	global_store_dwordx4 v0, v[160:163], s[30:31]
	s_mov_b32 exec_lo, 0xffffffff
	s_mov_b32 exec_hi, 0xffff
	v_lshlrev_b32_e32 v4, 16, v168
	v_and_b32_e32 v6, 0xffff0000, v168
	v_lshlrev_b32_e32 v7, 16, v169
	v_and_b32_e32 v24, 0xffff0000, v169
	v_lshlrev_b32_e32 v25, 16, v170
	v_and_b32_e32 v164, 0xffff0000, v170
	v_lshlrev_b32_e32 v165, 16, v171
	v_and_b32_e32 v192, 0xffff0000, v171
	v_add_f32_e32 v8, v8, v4
	v_add_f32_e32 v9, v9, v6
	v_add_f32_e32 v10, v10, v7
	v_add_f32_e32 v11, v11, v24
	v_add_f32_e32 v12, v12, v25
	v_add_f32_e32 v13, v13, v164
	v_add_f32_e32 v14, v14, v165
	v_add_f32_e32 v15, v15, v192
	s_mov_b32 exec_lo, -1
	s_mov_b32 exec_hi, -1
	v_lshlrev_b32_e32 v4, 16, v172
	v_and_b32_e32 v6, 0xffff0000, v172
	v_lshlrev_b32_e32 v7, 16, v173
	v_and_b32_e32 v24, 0xffff0000, v173
	v_lshlrev_b32_e32 v25, 16, v174
	v_and_b32_e32 v164, 0xffff0000, v174
	v_lshlrev_b32_e32 v165, 16, v175
	v_and_b32_e32 v192, 0xffff0000, v175
	v_sub_f32_e32 v8, v8, v4
	v_sub_f32_e32 v9, v9, v6
	v_sub_f32_e32 v10, v10, v7
	v_sub_f32_e32 v11, v11, v24
	v_sub_f32_e32 v12, v12, v25
	v_sub_f32_e32 v13, v13, v164
	v_sub_f32_e32 v14, v14, v165
	v_sub_f32_e32 v15, v15, v192
	global_load_dwordx4 v[160:163], v237, s[28:29]
	global_load_dwordx4 v[168:171], v36, s[28:29]
	global_load_dwordx4 v[172:175], v37, s[28:29]
	s_waitcnt vmcnt(9)
; __device__ __forceinline__ unsigned cvt_pk_bf16(float lo, float hi) { unsigned r; asm volatile("v_cvt_pk_bf16_f32 %0, %1, %2" : "=v"(r) : "v"(lo), "v"(hi)); return r; }
; __device__ __forceinline__ float bflo(unsigned w) { return __uint_as_float(w << 16); }
; __device__ __forceinline__ float bfhi(unsigned w) { return __uint_as_float(w & 0xffff0000u); }
; #define POOL_ACC(V_, sg) do { s0 += sg bflo(V_.x); s1 += sg bfhi(V_.x); s2 += sg bflo(V_.y); s3 += sg bfhi(V_.y); s4 += sg bflo(V_.z); s5 += sg bfhi(V_.z); s6 += sg bflo(V_.w); s7 += sg bfhi(V_.w); } while (0)
; __device__ __forceinline__ void pool_phase(const bf16_t* zp, bf16_t* mixed, const int wave_s) {
;     ...
;         for (int i = 0; i < 64; ++i) {
;             const int sp = pos0 + i, lo = max(sp - half, 0), hi = min(sp + half - 1, S - 1);
;             const float ic = 1.0f / (float)(hi - lo + 1);
;             const u32x4 w = *(const u32x4*)(zs + (size_t)sp * 512);
;             u32x4 o;
;             o.x = cvt_pk_bf16(s0 * ic - bflo(w.x), s1 * ic - bfhi(w.x)); o.y = cvt_pk_bf16(s2 * ic - bflo(w.y), s3 * ic - bfhi(w.y));
;             o.z = cvt_pk_bf16(s4 * ic - bflo(w.z), s5 * ic - bfhi(w.z)); o.w = cvt_pk_bf16(s6 * ic - bflo(w.w), s7 * ic - bfhi(w.w));
;             *(u32x4*)(ms + (size_t)sp * DM) = o;
;             const int jn = sp + half, jo = sp - half;
;             if (jn < S) { const u32x4 wn = *(const u32x4*)(zs + (size_t)jn * 512); POOL_ACC(wn, +); }
;             if (jo >= 0) { const u32x4 wo = *(const u32x4*)(zs + (size_t)jo * 512); POOL_ACC(wo, -); }
;         }
	v_add_u32_e32 v228, 7, v26
	v_lshlrev_b32_e32 v164, 1, v26
	v_min_u32_e32 v228, v228, v164
	v_cvt_f32_u32_e32 v228, v228
	v_div_scale_f32 v4, s[2:3], v228, v228, 1.0
	v_rcp_f32_e32 v6, v4
	v_div_scale_f32 v7, vcc, 1.0, v228, 1.0
	v_fma_f32 v24, -v4, v6, 1.0
	v_fmac_f32_e32 v6, v24, v6
	v_mul_f32_e32 v24, v7, v6
	v_fma_f32 v25, -v4, v24, v7
	v_fmac_f32_e32 v24, v25, v6
	v_fma_f32 v4, -v4, v24, v7
	v_div_fmas_f32 v6, v4, v6, v24
	v_div_fixup_f32 v228, v6, v228, 1.0
	v_lshlrev_b32_e32 v4, 16, v180
	v_and_b32_e32 v6, 0xffff0000, v180
	v_lshlrev_b32_e32 v7, 16, v181
	v_and_b32_e32 v24, 0xffff0000, v181
	v_lshlrev_b32_e32 v25, 16, v182
	v_and_b32_e32 v164, 0xffff0000, v182
	v_lshlrev_b32_e32 v165, 16, v183
	v_and_b32_e32 v192, 0xffff0000, v183
	v_fma_f32 v4, v8, v228, -v4
	v_fma_f32 v6, v9, v228, -v6
	v_fma_f32 v7, v10, v228, -v7
	v_fma_f32 v24, v11, v228, -v24
	v_fma_f32 v25, v12, v228, -v25
	v_fma_f32 v164, v13, v228, -v164
	v_fma_f32 v165, v14, v228, -v165
	v_fma_f32 v192, v15, v228, -v192
	v_cvt_pk_bf16_f32 v180, v4, v6
	v_cvt_pk_bf16_f32 v181, v7, v24
	v_cvt_pk_bf16_f32 v182, v25, v164
	v_cvt_pk_bf16_f32 v183, v165, v192
	global_store_dwordx4 v0, v[180:183], s[30:31] offset:2048
	s_add_u32 s30, s30, 0x1000
	s_addc_u32 s31, s31, 0
	s_mov_b32 exec_lo, 0xffffffff
	s_mov_b32 exec_hi, 0xffff
	v_lshlrev_b32_e32 v4, 16, v184
	v_and_b32_e32 v6, 0xffff0000, v184
	v_lshlrev_b32_e32 v7, 16, v185
	v_and_b32_e32 v24, 0xffff0000, v185
	v_lshlrev_b32_e32 v25, 16, v186
	v_and_b32_e32 v164, 0xffff0000, v186
	v_lshlrev_b32_e32 v165, 16, v187
	v_and_b32_e32 v192, 0xffff0000, v187
	v_add_f32_e32 v8, v8, v4
	v_add_f32_e32 v9, v9, v6
	v_add_f32_e32 v10, v10, v7
	v_add_f32_e32 v11, v11, v24
	v_add_f32_e32 v12, v12, v25
	v_add_f32_e32 v13, v13, v164
	v_add_f32_e32 v14, v14, v165
	v_add_f32_e32 v15, v15, v192
	s_mov_b32 exec_lo, -1
	s_mov_b32 exec_hi, -1
	v_lshlrev_b32_e32 v4, 16, v188
	v_and_b32_e32 v6, 0xffff0000, v188
	v_lshlrev_b32_e32 v7, 16, v189
	v_and_b32_e32 v24, 0xffff0000, v189
	v_lshlrev_b32_e32 v25, 16, v190
	v_and_b32_e32 v164, 0xffff0000, v190
	v_lshlrev_b32_e32 v165, 16, v191
	v_and_b32_e32 v192, 0xffff0000, v191
	v_sub_f32_e32 v8, v8, v4
	v_sub_f32_e32 v9, v9, v6
	v_sub_f32_e32 v10, v10, v7
	v_sub_f32_e32 v11, v11, v24
	v_sub_f32_e32 v12, v12, v25
	v_sub_f32_e32 v13, v13, v164
	v_sub_f32_e32 v14, v14, v165
	v_sub_f32_e32 v15, v15, v192
	global_load_dwordx4 v[180:183], v237, s[28:29] offset:1024
	global_load_dwordx4 v[184:187], v36, s[28:29] offset:1024
	global_load_dwordx4 v[188:191], v37, s[28:29] offset:1024
	s_waitcnt vmcnt(9)
	v_add_u32_e32 v228, 6, v26
	v_lshlrev_b32_e32 v164, 1, v26
	v_min_u32_e32 v228, v228, v164
	v_cvt_f32_u32_e32 v228, v228
	v_div_scale_f32 v4, s[2:3], v228, v228, 1.0
	v_rcp_f32_e32 v6, v4
	v_div_scale_f32 v7, vcc, 1.0, v228, 1.0
	v_fma_f32 v24, -v4, v6, 1.0
	v_fmac_f32_e32 v6, v24, v6
	v_mul_f32_e32 v24, v7, v6
	v_fma_f32 v25, -v4, v24, v7
	v_fmac_f32_e32 v24, v25, v6
	v_fma_f32 v4, -v4, v24, v7
	v_div_fmas_f32 v6, v4, v6, v24
	v_div_fixup_f32 v228, v6, v228, 1.0
	v_lshlrev_b32_e32 v4, 16, v246
	v_and_b32_e32 v6, 0xffff0000, v246
	v_lshlrev_b32_e32 v7, 16, v247
	v_and_b32_e32 v24, 0xffff0000, v247
	v_lshlrev_b32_e32 v25, 16, v248
	v_and_b32_e32 v164, 0xffff0000, v248
	v_lshlrev_b32_e32 v165, 16, v249
	v_and_b32_e32 v192, 0xffff0000, v249
	v_fma_f32 v4, v8, v228, -v4
	v_fma_f32 v6, v9, v228, -v6
	v_fma_f32 v7, v10, v228, -v7
	v_fma_f32 v24, v11, v228, -v24
	v_fma_f32 v25, v12, v228, -v25
	v_fma_f32 v164, v13, v228, -v164
	v_fma_f32 v165, v14, v228, -v165
	v_fma_f32 v192, v15, v228, -v192
	v_cvt_pk_bf16_f32 v246, v4, v6
	v_cvt_pk_bf16_f32 v247, v7, v24
	v_cvt_pk_bf16_f32 v248, v25, v164
	v_cvt_pk_bf16_f32 v249, v165, v192
	global_store_dwordx4 v0, v[246:249], s[30:31]
	s_mov_b32 exec_lo, 0xffffffff
	s_mov_b32 exec_hi, 0xffff
	v_lshlrev_b32_e32 v4, 16, v250
	v_and_b32_e32 v6, 0xffff0000, v250
	v_lshlrev_b32_e32 v7, 16, v251
	v_and_b32_e32 v24, 0xffff0000, v251
	v_lshlrev_b32_e32 v25, 16, v252
	v_and_b32_e32 v164, 0xffff0000, v252
	v_lshlrev_b32_e32 v165, 16, v253
	v_and_b32_e32 v192, 0xffff0000, v253
	v_add_f32_e32 v8, v8, v4
	v_add_f32_e32 v9, v9, v6
	v_add_f32_e32 v10, v10, v7
	v_add_f32_e32 v11, v11, v24
	v_add_f32_e32 v12, v12, v25
	v_add_f32_e32 v13, v13, v164
	v_add_f32_e32 v14, v14, v165
	v_add_f32_e32 v15, v15, v192
	s_mov_b32 exec_lo, -1
	s_mov_b32 exec_hi, -1
	v_lshlrev_b32_e32 v4, 16, v20
	v_and_b32_e32 v6, 0xffff0000, v20
	v_lshlrev_b32_e32 v7, 16, v21
	v_and_b32_e32 v24, 0xffff0000, v21
	v_lshlrev_b32_e32 v25, 16, v22
	v_and_b32_e32 v164, 0xffff0000, v22
	v_lshlrev_b32_e32 v165, 16, v23
	v_and_b32_e32 v192, 0xffff0000, v23
	v_sub_f32_e32 v8, v8, v4
	v_sub_f32_e32 v9, v9, v6
	v_sub_f32_e32 v10, v10, v7
	v_sub_f32_e32 v11, v11, v24
	v_sub_f32_e32 v12, v12, v25
	v_sub_f32_e32 v13, v13, v164
	v_sub_f32_e32 v14, v14, v165
	v_sub_f32_e32 v15, v15, v192
	global_load_dwordx4 v[246:249], v237, s[28:29] offset:2048
	global_load_dwordx4 v[250:253], v36, s[28:29] offset:2048
	global_load_dwordx4 v[20:23], v37, s[28:29] offset:2048
	s_waitcnt vmcnt(9)
; __device__ __forceinline__ unsigned cvt_pk_bf16(float lo, float hi) { unsigned r; asm volatile("v_cvt_pk_bf16_f32 %0, %1, %2" : "=v"(r) : "v"(lo), "v"(hi)); return r; }
; __device__ __forceinline__ float bflo(unsigned w) { return __uint_as_float(w << 16); }
; __device__ __forceinline__ float bfhi(unsigned w) { return __uint_as_float(w & 0xffff0000u); }
; #define POOL_ACC(V_, sg) do { s0 += sg bflo(V_.x); s1 += sg bfhi(V_.x); s2 += sg bflo(V_.y); s3 += sg bfhi(V_.y); s4 += sg bflo(V_.z); s5 += sg bfhi(V_.z); s6 += sg bflo(V_.w); s7 += sg bfhi(V_.w); } while (0)
; __device__ __forceinline__ void pool_phase(const bf16_t* zp, bf16_t* mixed, const int wave_s) {
;     ...
;         for (int i = 0; i < 64; ++i) {
;             const int sp = pos0 + i, lo = max(sp - half, 0), hi = min(sp + half - 1, S - 1);
;             const float ic = 1.0f / (float)(hi - lo + 1);
;             const u32x4 w = *(const u32x4*)(zs + (size_t)sp * 512);
;             u32x4 o;
;             o.x = cvt_pk_bf16(s0 * ic - bflo(w.x), s1 * ic - bfhi(w.x)); o.y = cvt_pk_bf16(s2 * ic - bflo(w.y), s3 * ic - bfhi(w.y));
;             o.z = cvt_pk_bf16(s4 * ic - bflo(w.z), s5 * ic - bfhi(w.z)); o.w = cvt_pk_bf16(s6 * ic - bflo(w.w), s7 * ic - bfhi(w.w));
;             *(u32x4*)(ms + (size_t)sp * DM) = o;
;             const int jn = sp + half, jo = sp - half;
;             if (jn < S) { const u32x4 wn = *(const u32x4*)(zs + (size_t)jn * 512); POOL_ACC(wn, +); }
;             if (jo >= 0) { const u32x4 wo = *(const u32x4*)(zs + (size_t)jo * 512); POOL_ACC(wo, -); }
;         }
	v_add_u32_e32 v228, 5, v26
	v_lshlrev_b32_e32 v164, 1, v26
	v_min_u32_e32 v228, v228, v164
	v_cvt_f32_u32_e32 v228, v228
	v_div_scale_f32 v4, s[2:3], v228, v228, 1.0
	v_rcp_f32_e32 v6, v4
	v_div_scale_f32 v7, vcc, 1.0, v228, 1.0
	v_fma_f32 v24, -v4, v6, 1.0
	v_fmac_f32_e32 v6, v24, v6
	v_mul_f32_e32 v24, v7, v6
	v_fma_f32 v25, -v4, v24, v7
	v_fmac_f32_e32 v24, v25, v6
	v_fma_f32 v4, -v4, v24, v7
	v_div_fmas_f32 v6, v4, v6, v24
	v_div_fixup_f32 v228, v6, v228, 1.0
	v_lshlrev_b32_e32 v4, 16, v28
	v_and_b32_e32 v6, 0xffff0000, v28
	v_lshlrev_b32_e32 v7, 16, v29
	v_and_b32_e32 v24, 0xffff0000, v29
	v_lshlrev_b32_e32 v25, 16, v30
	v_and_b32_e32 v164, 0xffff0000, v30
	v_lshlrev_b32_e32 v165, 16, v31
	v_and_b32_e32 v192, 0xffff0000, v31
	v_fma_f32 v4, v8, v228, -v4
	v_fma_f32 v6, v9, v228, -v6
	v_fma_f32 v7, v10, v228, -v7
	v_fma_f32 v24, v11, v228, -v24
	v_fma_f32 v25, v12, v228, -v25
	v_fma_f32 v164, v13, v228, -v164
	v_fma_f32 v165, v14, v228, -v165
	v_fma_f32 v192, v15, v228, -v192
	v_cvt_pk_bf16_f32 v28, v4, v6
	v_cvt_pk_bf16_f32 v29, v7, v24
	v_cvt_pk_bf16_f32 v30, v25, v164
	v_cvt_pk_bf16_f32 v31, v165, v192
	global_store_dwordx4 v0, v[28:31], s[30:31] offset:2048
	s_add_u32 s30, s30, 0x1000
	s_addc_u32 s31, s31, 0
	s_mov_b32 exec_lo, 0xffffffff
	s_mov_b32 exec_hi, 0xffff
	v_lshlrev_b32_e32 v4, 16, v32
	v_and_b32_e32 v6, 0xffff0000, v32
	v_lshlrev_b32_e32 v7, 16, v33
	v_and_b32_e32 v24, 0xffff0000, v33
	v_lshlrev_b32_e32 v25, 16, v34
	v_and_b32_e32 v164, 0xffff0000, v34
	v_lshlrev_b32_e32 v165, 16, v35
	v_and_b32_e32 v192, 0xffff0000, v35
	v_add_f32_e32 v8, v8, v4
	v_add_f32_e32 v9, v9, v6
	v_add_f32_e32 v10, v10, v7
	v_add_f32_e32 v11, v11, v24
	v_add_f32_e32 v12, v12, v25
	v_add_f32_e32 v13, v13, v164
	v_add_f32_e32 v14, v14, v165
	v_add_f32_e32 v15, v15, v192
	s_mov_b32 exec_lo, -1
	s_mov_b32 exec_hi, -1
	v_lshlrev_b32_e32 v4, 16, v16
	v_and_b32_e32 v6, 0xffff0000, v16
	v_lshlrev_b32_e32 v7, 16, v17
	v_and_b32_e32 v24, 0xffff0000, v17
	v_lshlrev_b32_e32 v25, 16, v18
	v_and_b32_e32 v164, 0xffff0000, v18
	v_lshlrev_b32_e32 v165, 16, v19
	v_and_b32_e32 v192, 0xffff0000, v19
	v_sub_f32_e32 v8, v8, v4
	v_sub_f32_e32 v9, v9, v6
	v_sub_f32_e32 v10, v10, v7
	v_sub_f32_e32 v11, v11, v24
	v_sub_f32_e32 v12, v12, v25
	v_sub_f32_e32 v13, v13, v164
	v_sub_f32_e32 v14, v14, v165
	v_sub_f32_e32 v15, v15, v192
	global_load_dwordx4 v[28:31], v237, s[28:29] offset:3072
	global_load_dwordx4 v[32:35], v36, s[28:29] offset:3072
	global_load_dwordx4 v[16:19], v37, s[28:29] offset:3072
	s_add_u32 s28, s28, 0x1000
	s_addc_u32 s29, s29, 0
	s_waitcnt vmcnt(9)
	v_add_u32_e32 v228, 4, v26
	v_lshlrev_b32_e32 v164, 1, v26
	v_min_u32_e32 v228, v228, v164
	v_cvt_f32_u32_e32 v228, v228
	v_div_scale_f32 v4, s[2:3], v228, v228, 1.0
	v_rcp_f32_e32 v6, v4
	v_div_scale_f32 v7, vcc, 1.0, v228, 1.0
	v_fma_f32 v24, -v4, v6, 1.0
	v_fmac_f32_e32 v6, v24, v6
	v_mul_f32_e32 v24, v7, v6
	v_fma_f32 v25, -v4, v24, v7
	v_fmac_f32_e32 v24, v25, v6
	v_fma_f32 v4, -v4, v24, v7
	v_div_fmas_f32 v6, v4, v6, v24
	v_div_fixup_f32 v228, v6, v228, 1.0
	v_lshlrev_b32_e32 v4, 16, v160
	v_and_b32_e32 v6, 0xffff0000, v160
	v_lshlrev_b32_e32 v7, 16, v161
	v_and_b32_e32 v24, 0xffff0000, v161
	v_lshlrev_b32_e32 v25, 16, v162
	v_and_b32_e32 v164, 0xffff0000, v162
	v_lshlrev_b32_e32 v165, 16, v163
	v_and_b32_e32 v192, 0xffff0000, v163
	v_fma_f32 v4, v8, v228, -v4
	v_fma_f32 v6, v9, v228, -v6
	v_fma_f32 v7, v10, v228, -v7
	v_fma_f32 v24, v11, v228, -v24
	v_fma_f32 v25, v12, v228, -v25
	v_fma_f32 v164, v13, v228, -v164
	v_fma_f32 v165, v14, v228, -v165
	v_fma_f32 v192, v15, v228, -v192
	v_cvt_pk_bf16_f32 v160, v4, v6
	v_cvt_pk_bf16_f32 v161, v7, v24
	v_cvt_pk_bf16_f32 v162, v25, v164
	v_cvt_pk_bf16_f32 v163, v165, v192
	global_store_dwordx4 v0, v[160:163], s[30:31]
	s_mov_b32 exec_lo, 0xffffffff
	s_mov_b32 exec_hi, 0x0
	v_lshlrev_b32_e32 v4, 16, v168
	v_and_b32_e32 v6, 0xffff0000, v168
	v_lshlrev_b32_e32 v7, 16, v169
	v_and_b32_e32 v24, 0xffff0000, v169
	v_lshlrev_b32_e32 v25, 16, v170
	v_and_b32_e32 v164, 0xffff0000, v170
	v_lshlrev_b32_e32 v165, 16, v171
	v_and_b32_e32 v192, 0xffff0000, v171
	v_add_f32_e32 v8, v8, v4
	v_add_f32_e32 v9, v9, v6
	v_add_f32_e32 v10, v10, v7
	v_add_f32_e32 v11, v11, v24
	v_add_f32_e32 v12, v12, v25
	v_add_f32_e32 v13, v13, v164
	v_add_f32_e32 v14, v14, v165
	v_add_f32_e32 v15, v15, v192
	s_mov_b32 exec_lo, -1
	s_mov_b32 exec_hi, -1
	v_lshlrev_b32_e32 v4, 16, v172
	v_and_b32_e32 v6, 0xffff0000, v172
	v_lshlrev_b32_e32 v7, 16, v173
	v_and_b32_e32 v24, 0xffff0000, v173
	v_lshlrev_b32_e32 v25, 16, v174
	v_and_b32_e32 v164, 0xffff0000, v174
	v_lshlrev_b32_e32 v165, 16, v175
	v_and_b32_e32 v192, 0xffff0000, v175
	v_sub_f32_e32 v8, v8, v4
	v_sub_f32_e32 v9, v9, v6
	v_sub_f32_e32 v10, v10, v7
	v_sub_f32_e32 v11, v11, v24
	v_sub_f32_e32 v12, v12, v25
	v_sub_f32_e32 v13, v13, v164
	v_sub_f32_e32 v14, v14, v165
	v_sub_f32_e32 v15, v15, v192
	global_load_dwordx4 v[160:163], v237, s[28:29]
	global_load_dwordx4 v[168:171], v36, s[28:29]
	global_load_dwordx4 v[172:175], v37, s[28:29]
	s_waitcnt vmcnt(9)
; __device__ __forceinline__ unsigned cvt_pk_bf16(float lo, float hi) { unsigned r; asm volatile("v_cvt_pk_bf16_f32 %0, %1, %2" : "=v"(r) : "v"(lo), "v"(hi)); return r; }
; __device__ __forceinline__ float bflo(unsigned w) { return __uint_as_float(w << 16); }
; __device__ __forceinline__ float bfhi(unsigned w) { return __uint_as_float(w & 0xffff0000u); }
; #define POOL_ACC(V_, sg) do { s0 += sg bflo(V_.x); s1 += sg bfhi(V_.x); s2 += sg bflo(V_.y); s3 += sg bfhi(V_.y); s4 += sg bflo(V_.z); s5 += sg bfhi(V_.z); s6 += sg bflo(V_.w); s7 += sg bfhi(V_.w); } while (0)
; __device__ __forceinline__ void pool_phase(const bf16_t* zp, bf16_t* mixed, const int wave_s) {
;     ...
;         for (int i = 0; i < 64; ++i) {
;             const int sp = pos0 + i, lo = max(sp - half, 0), hi = min(sp + half - 1, S - 1);
;             const float ic = 1.0f / (float)(hi - lo + 1);
;             const u32x4 w = *(const u32x4*)(zs + (size_t)sp * 512);
;             u32x4 o;
;             o.x = cvt_pk_bf16(s0 * ic - bflo(w.x), s1 * ic - bfhi(w.x)); o.y = cvt_pk_bf16(s2 * ic - bflo(w.y), s3 * ic - bfhi(w.y));
;             o.z = cvt_pk_bf16(s4 * ic - bflo(w.z), s5 * ic - bfhi(w.z)); o.w = cvt_pk_bf16(s6 * ic - bflo(w.w), s7 * ic - bfhi(w.w));
;             *(u32x4*)(ms + (size_t)sp * DM) = o;
;             const int jn = sp + half, jo = sp - half;
;             if (jn < S) { const u32x4 wn = *(const u32x4*)(zs + (size_t)jn * 512); POOL_ACC(wn, +); }
;             if (jo >= 0) { const u32x4 wo = *(const u32x4*)(zs + (size_t)jo * 512); POOL_ACC(wo, -); }
;         }
	v_add_u32_e32 v228, 3, v26
	v_lshlrev_b32_e32 v164, 1, v26
	v_min_u32_e32 v228, v228, v164
	v_cvt_f32_u32_e32 v228, v228
	v_div_scale_f32 v4, s[2:3], v228, v228, 1.0
	v_rcp_f32_e32 v6, v4
	v_div_scale_f32 v7, vcc, 1.0, v228, 1.0
	v_fma_f32 v24, -v4, v6, 1.0
	v_fmac_f32_e32 v6, v24, v6
	v_mul_f32_e32 v24, v7, v6
	v_fma_f32 v25, -v4, v24, v7
	v_fmac_f32_e32 v24, v25, v6
	v_fma_f32 v4, -v4, v24, v7
	v_div_fmas_f32 v6, v4, v6, v24
	v_div_fixup_f32 v228, v6, v228, 1.0
	v_lshlrev_b32_e32 v4, 16, v180
	v_and_b32_e32 v6, 0xffff0000, v180
	v_lshlrev_b32_e32 v7, 16, v181
	v_and_b32_e32 v24, 0xffff0000, v181
	v_lshlrev_b32_e32 v25, 16, v182
	v_and_b32_e32 v164, 0xffff0000, v182
	v_lshlrev_b32_e32 v165, 16, v183
	v_and_b32_e32 v192, 0xffff0000, v183
	v_fma_f32 v4, v8, v228, -v4
	v_fma_f32 v6, v9, v228, -v6
	v_fma_f32 v7, v10, v228, -v7
	v_fma_f32 v24, v11, v228, -v24
	v_fma_f32 v25, v12, v228, -v25
	v_fma_f32 v164, v13, v228, -v164
	v_fma_f32 v165, v14, v228, -v165
	v_fma_f32 v192, v15, v228, -v192
	v_cvt_pk_bf16_f32 v180, v4, v6
	v_cvt_pk_bf16_f32 v181, v7, v24
	v_cvt_pk_bf16_f32 v182, v25, v164
	v_cvt_pk_bf16_f32 v183, v165, v192
	global_store_dwordx4 v0, v[180:183], s[30:31] offset:2048
	s_add_u32 s30, s30, 0x1000
	s_addc_u32 s31, s31, 0
	s_mov_b32 exec_lo, 0xffffffff
	s_mov_b32 exec_hi, 0x0
	v_lshlrev_b32_e32 v4, 16, v184
	v_and_b32_e32 v6, 0xffff0000, v184
	v_lshlrev_b32_e32 v7, 16, v185
	v_and_b32_e32 v24, 0xffff0000, v185
	v_lshlrev_b32_e32 v25, 16, v186
	v_and_b32_e32 v164, 0xffff0000, v186
	v_lshlrev_b32_e32 v165, 16, v187
	v_and_b32_e32 v192, 0xffff0000, v187
	v_add_f32_e32 v8, v8, v4
	v_add_f32_e32 v9, v9, v6
	v_add_f32_e32 v10, v10, v7
	v_add_f32_e32 v11, v11, v24
	v_add_f32_e32 v12, v12, v25
	v_add_f32_e32 v13, v13, v164
	v_add_f32_e32 v14, v14, v165
	v_add_f32_e32 v15, v15, v192
	s_mov_b32 exec_lo, -1
	s_mov_b32 exec_hi, -1
	v_lshlrev_b32_e32 v4, 16, v188
	v_and_b32_e32 v6, 0xffff0000, v188
	v_lshlrev_b32_e32 v7, 16, v189
	v_and_b32_e32 v24, 0xffff0000, v189
	v_lshlrev_b32_e32 v25, 16, v190
	v_and_b32_e32 v164, 0xffff0000, v190
	v_lshlrev_b32_e32 v165, 16, v191
	v_and_b32_e32 v192, 0xffff0000, v191
	v_sub_f32_e32 v8, v8, v4
	v_sub_f32_e32 v9, v9, v6
	v_sub_f32_e32 v10, v10, v7
	v_sub_f32_e32 v11, v11, v24
	v_sub_f32_e32 v12, v12, v25
	v_sub_f32_e32 v13, v13, v164
	v_sub_f32_e32 v14, v14, v165
	v_sub_f32_e32 v15, v15, v192
	global_load_dwordx4 v[180:183], v237, s[28:29] offset:1024
	global_load_dwordx4 v[184:187], v36, s[28:29] offset:1024
	global_load_dwordx4 v[188:191], v37, s[28:29] offset:1024
	s_waitcnt vmcnt(9)
	v_add_u32_e32 v228, 2, v26
	v_lshlrev_b32_e32 v164, 1, v26
	v_min_u32_e32 v228, v228, v164
	v_cvt_f32_u32_e32 v228, v228
	v_div_scale_f32 v4, s[2:3], v228, v228, 1.0
	v_rcp_f32_e32 v6, v4
	v_div_scale_f32 v7, vcc, 1.0, v228, 1.0
	v_fma_f32 v24, -v4, v6, 1.0
	v_fmac_f32_e32 v6, v24, v6
	v_mul_f32_e32 v24, v7, v6
	v_fma_f32 v25, -v4, v24, v7
	v_fmac_f32_e32 v24, v25, v6
	v_fma_f32 v4, -v4, v24, v7
	v_div_fmas_f32 v6, v4, v6, v24
	v_div_fixup_f32 v228, v6, v228, 1.0
	v_lshlrev_b32_e32 v4, 16, v246
	v_and_b32_e32 v6, 0xffff0000, v246
	v_lshlrev_b32_e32 v7, 16, v247
	v_and_b32_e32 v24, 0xffff0000, v247
	v_lshlrev_b32_e32 v25, 16, v248
	v_and_b32_e32 v164, 0xffff0000, v248
	v_lshlrev_b32_e32 v165, 16, v249
	v_and_b32_e32 v192, 0xffff0000, v249
	v_fma_f32 v4, v8, v228, -v4
	v_fma_f32 v6, v9, v228, -v6
	v_fma_f32 v7, v10, v228, -v7
	v_fma_f32 v24, v11, v228, -v24
	v_fma_f32 v25, v12, v228, -v25
	v_fma_f32 v164, v13, v228, -v164
	v_fma_f32 v165, v14, v228, -v165
	v_fma_f32 v192, v15, v228, -v192
	v_cvt_pk_bf16_f32 v246, v4, v6
	v_cvt_pk_bf16_f32 v247, v7, v24
	v_cvt_pk_bf16_f32 v248, v25, v164
	v_cvt_pk_bf16_f32 v249, v165, v192
	global_store_dwordx4 v0, v[246:249], s[30:31]
	s_mov_b32 exec_lo, 0xffff
	s_mov_b32 exec_hi, 0x0
	v_lshlrev_b32_e32 v4, 16, v250
	v_and_b32_e32 v6, 0xffff0000, v250
	v_lshlrev_b32_e32 v7, 16, v251
	v_and_b32_e32 v24, 0xffff0000, v251
	v_lshlrev_b32_e32 v25, 16, v252
	v_and_b32_e32 v164, 0xffff0000, v252
	v_lshlrev_b32_e32 v165, 16, v253
	v_and_b32_e32 v192, 0xffff0000, v253
	v_add_f32_e32 v8, v8, v4
	v_add_f32_e32 v9, v9, v6
	v_add_f32_e32 v10, v10, v7
	v_add_f32_e32 v11, v11, v24
	v_add_f32_e32 v12, v12, v25
	v_add_f32_e32 v13, v13, v164
	v_add_f32_e32 v14, v14, v165
	v_add_f32_e32 v15, v15, v192
	s_mov_b32 exec_lo, -1
	s_mov_b32 exec_hi, -1
	v_lshlrev_b32_e32 v4, 16, v20
	v_and_b32_e32 v6, 0xffff0000, v20
	v_lshlrev_b32_e32 v7, 16, v21
	v_and_b32_e32 v24, 0xffff0000, v21
	v_lshlrev_b32_e32 v25, 16, v22
	v_and_b32_e32 v164, 0xffff0000, v22
	v_lshlrev_b32_e32 v165, 16, v23
	v_and_b32_e32 v192, 0xffff0000, v23
	v_sub_f32_e32 v8, v8, v4
	v_sub_f32_e32 v9, v9, v6
	v_sub_f32_e32 v10, v10, v7
	v_sub_f32_e32 v11, v11, v24
	v_sub_f32_e32 v12, v12, v25
	v_sub_f32_e32 v13, v13, v164
	v_sub_f32_e32 v14, v14, v165
	v_sub_f32_e32 v15, v15, v192
	global_load_dwordx4 v[246:249], v237, s[28:29] offset:2048
	global_load_dwordx4 v[250:253], v36, s[28:29] offset:2048
	global_load_dwordx4 v[20:23], v37, s[28:29] offset:2048
	s_waitcnt vmcnt(9)
; __device__ __forceinline__ unsigned cvt_pk_bf16(float lo, float hi) { unsigned r; asm volatile("v_cvt_pk_bf16_f32 %0, %1, %2" : "=v"(r) : "v"(lo), "v"(hi)); return r; }
; __device__ __forceinline__ float bflo(unsigned w) { return __uint_as_float(w << 16); }
; __device__ __forceinline__ float bfhi(unsigned w) { return __uint_as_float(w & 0xffff0000u); }
; #define POOL_ACC(V_, sg) do { s0 += sg bflo(V_.x); s1 += sg bfhi(V_.x); s2 += sg bflo(V_.y); s3 += sg bfhi(V_.y); s4 += sg bflo(V_.z); s5 += sg bfhi(V_.z); s6 += sg bflo(V_.w); s7 += sg bfhi(V_.w); } while (0)
; __device__ __forceinline__ void pool_phase(const bf16_t* zp, bf16_t* mixed, const int wave_s) {
;     ...
;         for (int d = -8; d < 8; ++d) { const int j = pos0 + d; if (d >= -half && d < half && j >= 0 && j < S) { const u32x4 w = *(const u32x4*)(zs + (size_t)j * 512); POOL_ACC(w, +); } }
;     ...
;         for (int i = 0; i < 64; ++i) {
;             const int sp = pos0 + i, lo = max(sp - half, 0), hi = min(sp + half - 1, S - 1);
;             const float ic = 1.0f / (float)(hi - lo + 1);
;             const u32x4 w = *(const u32x4*)(zs + (size_t)sp * 512);
;             u32x4 o;
;             o.x = cvt_pk_bf16(s0 * ic - bflo(w.x), s1 * ic - bfhi(w.x)); o.y = cvt_pk_bf16(s2 * ic - bflo(w.y), s3 * ic - bfhi(w.y));
;             o.z = cvt_pk_bf16(s4 * ic - bflo(w.z), s5 * ic - bfhi(w.z)); o.w = cvt_pk_bf16(s6 * ic - bflo(w.w), s7 * ic - bfhi(w.w));
;             *(u32x4*)(ms + (size_t)sp * DM) = o;
;             const int jn = sp + half, jo = sp - half;
;             if (jn < S) { const u32x4 wn = *(const u32x4*)(zs + (size_t)jn * 512); POOL_ACC(wn, +); }
;             if (jo >= 0) { const u32x4 wo = *(const u32x4*)(zs + (size_t)jo * 512); POOL_ACC(wo, -); }
;         }
	v_add_u32_e32 v228, 1, v26
	v_lshlrev_b32_e32 v164, 1, v26
	v_min_u32_e32 v228, v228, v164
	v_cvt_f32_u32_e32 v228, v228
	v_div_scale_f32 v4, s[2:3], v228, v228, 1.0
	v_rcp_f32_e32 v6, v4
	v_div_scale_f32 v7, vcc, 1.0, v228, 1.0
	v_fma_f32 v24, -v4, v6, 1.0
	v_fmac_f32_e32 v6, v24, v6
	v_mul_f32_e32 v24, v7, v6
	v_fma_f32 v25, -v4, v24, v7
	v_fmac_f32_e32 v24, v25, v6
	v_fma_f32 v4, -v4, v24, v7
	v_div_fmas_f32 v6, v4, v6, v24
	v_div_fixup_f32 v228, v6, v228, 1.0
	v_lshlrev_b32_e32 v4, 16, v28
	v_and_b32_e32 v6, 0xffff0000, v28
	v_lshlrev_b32_e32 v7, 16, v29
	v_and_b32_e32 v24, 0xffff0000, v29
	v_lshlrev_b32_e32 v25, 16, v30
	v_and_b32_e32 v164, 0xffff0000, v30
	v_lshlrev_b32_e32 v165, 16, v31
	v_and_b32_e32 v192, 0xffff0000, v31
	v_fma_f32 v4, v8, v228, -v4
	v_fma_f32 v6, v9, v228, -v6
	v_fma_f32 v7, v10, v228, -v7
	v_fma_f32 v24, v11, v228, -v24
	v_fma_f32 v25, v12, v228, -v25
	v_fma_f32 v164, v13, v228, -v164
	v_fma_f32 v165, v14, v228, -v165
	v_fma_f32 v192, v15, v228, -v192
	v_cvt_pk_bf16_f32 v28, v4, v6
	v_cvt_pk_bf16_f32 v29, v7, v24
	v_cvt_pk_bf16_f32 v30, v25, v164
	v_cvt_pk_bf16_f32 v31, v165, v192
	global_store_dwordx4 v0, v[28:31], s[30:31] offset:2048
	s_add_u32 s30, s30, 0x1000
	s_addc_u32 s31, s31, 0
	v_lshlrev_b32_e32 v4, 16, v16
	v_and_b32_e32 v6, 0xffff0000, v16
	v_lshlrev_b32_e32 v7, 16, v17
	v_and_b32_e32 v24, 0xffff0000, v17
	v_lshlrev_b32_e32 v25, 16, v18
	v_and_b32_e32 v164, 0xffff0000, v18
	v_lshlrev_b32_e32 v165, 16, v19
	v_and_b32_e32 v192, 0xffff0000, v19
	v_sub_f32_e32 v8, v8, v4
	v_sub_f32_e32 v9, v9, v6
	v_sub_f32_e32 v10, v10, v7
	v_sub_f32_e32 v11, v11, v24
	v_sub_f32_e32 v12, v12, v25
	v_sub_f32_e32 v13, v13, v164
	v_sub_f32_e32 v14, v14, v165
	v_sub_f32_e32 v15, v15, v192
	global_load_dwordx4 v[28:31], v237, s[28:29] offset:3072
	global_load_dwordx4 v[32:35], v36, s[28:29] offset:3072
	global_load_dwordx4 v[16:19], v37, s[28:29] offset:3072
	s_add_u32 s28, s28, 0x1000
	s_addc_u32 s29, s29, 0
	s_waitcnt vmcnt(0)
	s_branch .LBB0_311
	s_sub_i32 s28, s3, s2
	s_ashr_i32 s29, s28, 31
	s_lshl_b64 s[28:29], s[28:29], 10
	s_add_i32 s26, s2, -8
	s_cmp_lt_u32 s26, s40
	v_lshl_add_u64 v[6:7], v[2:3], 0, s[28:29]
	s_cselect_b64 s[28:29], -1, 0
	v_mov_b32_e32 v4, v5
	s_and_b64 s[30:31], s[0:1], s[28:29]
	v_mov_b64_e32 v[14:15], v[4:5]
	v_mov_b64_e32 v[8:9], v[4:5]
	v_mov_b64_e32 v[10:11], v[4:5]
	v_mov_b64_e32 v[12:13], v[4:5]
	s_and_saveexec_b64 s[28:29], s[30:31]
	s_cbranch_execz .LBB0_314
	s_lshl_b64 s[30:31], s[26:27], 10
	v_lshl_add_u64 v[8:9], v[6:7], 0, s[30:31]
	global_load_dwordx4 v[8:11], v[8:9], off
	s_waitcnt vmcnt(0)
	v_and_b32_e32 v12, 0xffff0000, v8
	v_lshlrev_b32_e32 v13, 16, v8
	v_and_b32_e32 v8, 0xffff0000, v9
	v_lshlrev_b32_e32 v9, 16, v9
	v_and_b32_e32 v14, 0xffff0000, v10
	v_lshlrev_b32_e32 v15, 16, v10
	v_and_b32_e32 v16, 0xffff0000, v11
	v_lshlrev_b32_e32 v17, 16, v11
	v_pk_add_f32 v[12:13], v[12:13], 0 op_sel_hi:[1,0]
	v_pk_add_f32 v[10:11], v[8:9], 0 op_sel_hi:[1,0]
	v_pk_add_f32 v[8:9], v[14:15], 0 op_sel_hi:[1,0]
	v_pk_add_f32 v[14:15], v[16:17], 0 op_sel_hi:[1,0]
